# stack: v79 barrier edit + unused release-word atomic removed + GLA cum tile XOR swizzle (LDS bank conflicts)
# baseline (speedup 1.0000x reference)
.LBB0_1311:
	v_lshlrev_b32_e32 v86, 2, v10
	v_and_b32_e32 v87, 0x1fc, v86
	v_add_u32_e32 v104, 0, v87
	v_add_u32_e32 v107, s92, v86
	v_add_u32_e32 v106, s92, v87
	s_nop 0
	v_mfma_f32_16x16x32_bf16 v[86:89], v[76:79], v[72:75], 0
	v_lshlrev_b32_e32 v84, 9, v92
	v_and_b32_e32 v85, 0xffffffc0, v10
	v_add3_u32 v85, 0, v84, v85
	v_add_u32_e32 v108, v85, v8
	v_ashrrev_i32_e32 v84, 7, v10
	s_nop 0
	s_nop 1
	v_add_f32_e32 v90, v80, v86
	v_add_f32_e32 v87, v81, v87
	v_min_f32_e32 v86, 0, v90
	v_mul_f32_e64 v90, |v90|, s43
	v_mul_f32_e64 v91, |v87|, s43
	v_add_f32_e32 v95, v82, v88
	v_add_f32_e32 v89, v83, v89
	v_exp_f32_e32 v90, v90
	v_exp_f32_e32 v91, v91
	v_min_f32_e32 v88, 0, v95
	v_mul_f32_e64 v95, |v95|, s43
	v_mul_f32_e64 v96, |v89|, s43
	v_exp_f32_e32 v95, v95
	v_exp_f32_e32 v96, v96
	v_add_f32_e32 v90, 1.0, v90
	v_add_f32_e32 v91, 1.0, v91
	v_log_f32_e32 v90, v90
	v_log_f32_e32 v91, v91
	v_add_f32_e32 v95, 1.0, v95
	v_add_f32_e32 v96, 1.0, v96
	v_log_f32_e32 v95, v95
	v_log_f32_e32 v96, v96
	v_min_f32_e32 v87, 0, v87
	v_xor_b32_e32 v91, 0x80000000, v91
	v_xor_b32_e32 v90, 0x80000000, v90
	v_min_f32_e32 v89, 0, v89
	v_pk_fma_f32 v[86:87], v[90:91], s[46:47], v[86:87] op_sel_hi:[1,0,1]
	v_xor_b32_e32 v91, 0x80000000, v96
	v_xor_b32_e32 v90, 0x80000000, v95
	v_pk_fma_f32 v[88:89], v[90:91], s[46:47], v[88:89] op_sel_hi:[1,0,1]
	v_pk_mul_f32 v[86:87], v[86:87], s[50:51] op_sel_hi:[1,0]
	v_pk_mul_f32 v[88:89], v[88:89], s[50:51] op_sel_hi:[1,0]
	v_lshlrev_b32_e32 v236, 3, v204
	v_and_b32_e32 v236, 0x30, v236
	v_xor_b32_e32 v236, v236, v108
	ds_write_b128 v236, v[86:89]
	v_mfma_f32_16x16x32_bf16 v[86:89], v[76:79], v[68:71], 0
	v_lshlrev_b32_e32 v105, 13, v84
	v_cmp_lt_i32_e64 s[10:11], 0, v84
	v_mov_b32_e32 v117, 0
	s_nop 4
	v_add_f32_e32 v85, v81, v87
	v_mul_f32_e64 v87, |v85|, s43
	v_exp_f32_e32 v90, v87
	v_add_f32_e32 v8, v80, v86
	v_min_f32_e32 v87, 0, v85
	v_min_f32_e32 v86, 0, v8
	v_add_f32_e32 v85, 1.0, v90
	v_add_f32_e32 v90, v82, v88
	v_mul_f32_e64 v8, |v8|, s43
	v_min_f32_e32 v88, 0, v90
	v_mul_f32_e64 v90, |v90|, s43
	v_add_f32_e32 v89, v83, v89
	v_exp_f32_e32 v8, v8
	v_exp_f32_e32 v90, v90
	v_mul_f32_e64 v91, |v89|, s43
	v_exp_f32_e32 v91, v91
	v_add_f32_e32 v8, 1.0, v8
	v_add_f32_e32 v90, 1.0, v90
	v_log_f32_e32 v8, v8
	v_log_f32_e32 v85, v85
	v_log_f32_e32 v95, v90
	v_add_f32_e32 v90, 1.0, v91
	v_log_f32_e32 v96, v90
	v_xor_b32_e32 v91, 0x80000000, v85
	v_xor_b32_e32 v90, 0x80000000, v8
	v_min_f32_e32 v89, 0, v89
	v_pk_fma_f32 v[86:87], v[90:91], s[46:47], v[86:87] op_sel_hi:[1,0,1]
	v_xor_b32_e32 v91, 0x80000000, v96
	v_xor_b32_e32 v90, 0x80000000, v95
	v_pk_fma_f32 v[88:89], v[90:91], s[46:47], v[88:89] op_sel_hi:[1,0,1]
	v_pk_mul_f32 v[86:87], v[86:87], s[50:51] op_sel_hi:[1,0]
	v_pk_mul_f32 v[88:89], v[88:89], s[50:51] op_sel_hi:[1,0]
	v_lshlrev_b32_e32 v237, 3, v204
	v_and_b32_e32 v237, 0x30, v237
	v_xor_b32_e32 v237, v237, v108
	ds_write_b128 v237, v[86:89] offset:8192
	v_mfma_f32_16x16x32_bf16 v[86:89], v[76:79], v[60:63], 0
	v_mfma_f32_16x16x32_bf16 v[76:79], v[76:79], v[52:55], 0
	s_nop 6
	v_add_f32_e32 v85, v81, v87
	v_mul_f32_e64 v87, |v85|, s43
	v_exp_f32_e32 v90, v87
	v_add_f32_e32 v8, v80, v86
	v_min_f32_e32 v86, 0, v8
	v_mul_f32_e64 v8, |v8|, s43
	v_exp_f32_e32 v8, v8
	v_min_f32_e32 v87, 0, v85
	v_add_f32_e32 v85, 1.0, v90
	v_add_f32_e32 v90, v82, v88
	v_min_f32_e32 v88, 0, v90
	v_mul_f32_e64 v90, |v90|, s43
	v_add_f32_e32 v89, v83, v89
	v_exp_f32_e32 v90, v90
	v_mul_f32_e64 v91, |v89|, s43
	v_add_f32_e32 v8, 1.0, v8
	v_exp_f32_e32 v91, v91
	v_log_f32_e32 v8, v8
	v_add_f32_e32 v90, 1.0, v90
	v_log_f32_e32 v95, v90
	v_add_f32_e32 v90, 1.0, v91
	v_log_f32_e32 v96, v90
	v_xor_b32_e32 v90, 0x80000000, v8
	v_add_f32_e32 v8, v80, v76
	v_add_f32_e32 v77, v81, v77
	v_add_f32_e32 v81, v82, v78
	v_min_f32_e32 v76, 0, v8
	v_mul_f32_e64 v8, |v8|, s43
	v_mul_f32_e64 v80, |v77|, s43
	v_min_f32_e32 v78, 0, v81
	v_mul_f32_e64 v81, |v81|, s43
	v_add_f32_e32 v79, v83, v79
	v_exp_f32_e32 v8, v8
	v_exp_f32_e32 v80, v80
	v_exp_f32_e32 v81, v81
	v_mul_f32_e64 v82, |v79|, s43
	v_exp_f32_e32 v82, v82
	v_add_f32_e32 v8, 1.0, v8
	v_add_f32_e32 v80, 1.0, v80
	v_add_f32_e32 v81, 1.0, v81
	v_log_f32_e32 v85, v85
	v_log_f32_e32 v8, v8
	v_log_f32_e32 v80, v80
	v_log_f32_e32 v83, v81
	v_add_f32_e32 v81, 1.0, v82
	v_log_f32_e32 v82, v81
	v_xor_b32_e32 v91, 0x80000000, v85
	v_min_f32_e32 v77, 0, v77
	v_xor_b32_e32 v81, 0x80000000, v80
	v_xor_b32_e32 v80, 0x80000000, v8
	v_min_f32_e32 v89, 0, v89
	v_pk_fma_f32 v[86:87], v[90:91], s[46:47], v[86:87] op_sel_hi:[1,0,1]
	v_xor_b32_e32 v91, 0x80000000, v96
	v_xor_b32_e32 v90, 0x80000000, v95
	v_min_f32_e32 v79, 0, v79
	v_pk_fma_f32 v[76:77], v[80:81], s[46:47], v[76:77] op_sel_hi:[1,0,1]
	v_xor_b32_e32 v81, 0x80000000, v82
	v_xor_b32_e32 v80, 0x80000000, v83
	v_pk_fma_f32 v[88:89], v[90:91], s[46:47], v[88:89] op_sel_hi:[1,0,1]
	v_pk_fma_f32 v[78:79], v[80:81], s[46:47], v[78:79] op_sel_hi:[1,0,1]
	v_pk_mul_f32 v[88:89], v[88:89], s[50:51] op_sel_hi:[1,0]
	v_pk_mul_f32 v[86:87], v[86:87], s[50:51] op_sel_hi:[1,0]
	v_pk_mul_f32 v[78:79], v[78:79], s[50:51] op_sel_hi:[1,0]
	v_pk_mul_f32 v[76:77], v[76:77], s[50:51] op_sel_hi:[1,0]
	v_add_u32_e32 v8, v104, v105
	v_lshlrev_b32_e32 v236, 3, v204
	v_and_b32_e32 v236, 0x30, v236
	v_xor_b32_e32 v236, v236, v108
	ds_write_b128 v236, v[86:89] offset:16384
	v_lshlrev_b32_e32 v237, 3, v204
	v_and_b32_e32 v237, 0x30, v237
	v_xor_b32_e32 v237, v237, v108
	ds_write_b128 v237, v[76:79] offset:24576
	s_waitcnt lgkmcnt(0)
	s_barrier
	ds_read2st64_b32 v[76:77], v8 offset1:2
	v_xor_b32_e32 v236, 16, v8
	ds_read2st64_b32 v[78:79], v236 offset0:4 offset1:6
	v_xor_b32_e32 v237, 32, v8
	ds_read2st64_b32 v[80:81], v237 offset0:8 offset1:10
	v_xor_b32_e32 v236, 48, v8
	ds_read2st64_b32 v[82:83], v236 offset0:12 offset1:14
	ds_read2st64_b32 v[86:87], v8 offset0:16 offset1:18
	v_xor_b32_e32 v237, 16, v8
	ds_read2st64_b32 v[88:89], v237 offset0:20 offset1:22
	v_xor_b32_e32 v236, 32, v8
	ds_read2st64_b32 v[90:91], v236 offset0:24 offset1:26
	v_xor_b32_e32 v237, 48, v8
	ds_read2st64_b32 v[118:119], v237 offset0:28 offset1:30
	s_waitcnt lgkmcnt(7)
	v_add_f32_e32 v115, 0, v76
	v_add_f32_e32 v116, v115, v77
	s_waitcnt lgkmcnt(6)
	v_add_f32_e32 v113, v116, v78
	v_add_f32_e32 v114, v113, v79
	s_waitcnt lgkmcnt(5)
	v_add_f32_e32 v111, v114, v80
	v_add_f32_e32 v112, v111, v81
	s_waitcnt lgkmcnt(4)
	v_add_f32_e32 v101, v112, v82
	v_add_f32_e32 v109, v101, v83
	s_waitcnt lgkmcnt(3)
	v_add_f32_e32 v99, v109, v86
	v_add_f32_e32 v100, v99, v87
	s_waitcnt lgkmcnt(2)
	v_add_f32_e32 v97, v100, v88
	v_add_f32_e32 v98, v97, v89
	s_waitcnt lgkmcnt(1)
	v_add_f32_e32 v95, v98, v90
	v_add_f32_e32 v96, v95, v91
	s_waitcnt lgkmcnt(0)
	v_add_f32_e32 v90, v96, v118
	v_add_f32_e32 v91, v90, v119
	ds_write_b32 v107, v91
	s_waitcnt lgkmcnt(0)
	s_barrier
	s_and_saveexec_b64 s[12:13], s[10:11]
	s_cbranch_execnz .LBB0_1366
	s_or_b64 exec, exec, s[12:13]
	v_cmp_lt_i32_e64 s[14:15], 1, v84
	s_and_saveexec_b64 s[12:13], s[14:15]
	s_cbranch_execnz .LBB0_1367

.LBB0_1315:
	s_or_b64 exec, exec, s[12:13]
	v_lshlrev_b32_e32 v110, 3, v10
	v_and_b32_e32 v120, 0x78, v110
	v_ashrrev_i32_e32 v128, 4, v10
	v_add_f32_e32 v115, v115, v117
	v_add_f32_e32 v116, v116, v117
	v_add_f32_e32 v113, v113, v117
	v_add_f32_e32 v114, v114, v117
	v_add_f32_e32 v111, v111, v117
	v_add_f32_e32 v112, v112, v117
	v_add_f32_e32 v101, v101, v117
	v_add_f32_e32 v109, v109, v117
	v_add_f32_e32 v99, v99, v117
	v_add_f32_e32 v100, v100, v117
	v_add_f32_e32 v97, v97, v117
	v_add_f32_e32 v98, v98, v117
	v_add_f32_e32 v95, v95, v117
	v_add_f32_e32 v96, v96, v117
	v_add_f32_e32 v90, v90, v117
	v_add_f32_e32 v91, v91, v117
	v_lshl_add_u32 v110, v120, 2, 0
	ds_write2st64_b32 v8, v115, v116 offset1:2
	v_xor_b32_e32 v236, 16, v8
	ds_write2st64_b32 v236, v113, v114 offset0:4 offset1:6
	v_xor_b32_e32 v237, 32, v8
	ds_write2st64_b32 v237, v111, v112 offset0:8 offset1:10
	v_xor_b32_e32 v236, 48, v8
	ds_write2st64_b32 v236, v101, v109 offset0:12 offset1:14
	ds_write2st64_b32 v8, v99, v100 offset0:16 offset1:18
	v_xor_b32_e32 v237, 16, v8
	ds_write2st64_b32 v237, v97, v98 offset0:20 offset1:22
	v_xor_b32_e32 v236, 32, v8
	ds_write2st64_b32 v236, v95, v96 offset0:24 offset1:26
	v_xor_b32_e32 v237, 48, v8
	ds_write2st64_b32 v237, v90, v91 offset0:28 offset1:30
	v_lshlrev_b32_e32 v8, 9, v128
	v_add_u32_e32 v114, v110, v8
	s_waitcnt lgkmcnt(0)
	s_barrier
	v_xor_b32_e32 v236, 48, v110
	ds_read_b128 v[96:99], v236 offset:32256
	v_lshrrev_b32_e32 v237, 1, v204
	v_and_b32_e32 v237, 0x30, v237
	v_xor_b32_e32 v237, v237, v114
	ds_read_b128 v[116:119], v237
	v_lshlrev_b32_e32 v90, 1, v120
	v_xor_b32_e32 v236, 32, v110
	ds_read_b128 v[120:123], v236 offset:32256
	v_lshrrev_b32_e32 v237, 1, v204
	v_and_b32_e32 v237, 0x30, v237
	v_xor_b32_e32 v237, 16, v237
	v_xor_b32_e32 v237, v237, v114
	ds_read_b128 v[124:127], v237
	v_sub_u32_e32 v95, v110, v90
	v_lshlrev_b32_e32 v82, 16, v32
	s_waitcnt lgkmcnt(2)
	v_sub_f32_e32 v90, v96, v116
	v_sub_f32_e32 v91, v97, v117
	s_waitcnt lgkmcnt(0)
	v_sub_f32_e32 v109, v120, v124
	v_mul_f32_e32 v109, 0x3fb8aa3b, v109
	v_exp_f32_e32 v112, v109
	v_sub_f32_e32 v109, v121, v125
	v_mul_f32_e32 v109, 0x3fb8aa3b, v109
	v_exp_f32_e32 v113, v109
	v_sub_f32_e32 v109, v122, v126
	v_mul_f32_e32 v109, 0x3fb8aa3b, v109
	v_mul_f32_e32 v90, 0x3fb8aa3b, v90
	v_mul_f32_e32 v91, 0x3fb8aa3b, v91
	v_sub_f32_e32 v100, v98, v118
	v_sub_f32_e32 v101, v99, v119
	v_exp_f32_e32 v116, v109
	v_sub_f32_e32 v109, v123, v127
	v_exp_f32_e32 v90, v90
	v_exp_f32_e32 v91, v91
	v_mul_f32_e32 v100, 0x3fb8aa3b, v100
	v_mul_f32_e32 v101, 0x3fb8aa3b, v101
	v_mul_f32_e32 v109, 0x3fb8aa3b, v109
	v_exp_f32_e32 v100, v100
	v_exp_f32_e32 v101, v101
	v_exp_f32_e32 v117, v109
	v_and_b32_e32 v83, 0xffff0000, v32
	v_lshlrev_b32_e32 v84, 16, v33
	v_and_b32_e32 v85, 0xffff0000, v33
	v_lshlrev_b32_e32 v86, 16, v34
	v_and_b32_e32 v87, 0xffff0000, v34
	v_lshlrev_b32_e32 v88, 16, v35
	v_and_b32_e32 v89, 0xffff0000, v35
	v_pk_mul_f32 v[90:91], v[90:91], v[82:83]
	v_pk_mul_f32 v[100:101], v[100:101], v[84:85]
	v_pk_mul_f32 v[112:113], v[112:113], v[86:87]
	v_pk_mul_f32 v[124:125], v[116:117], v[88:89]
	v_cvt_pk_bf16_f32 v116, v90, v91
	v_mul_lo_u32 v90, v128, s45
	v_cvt_pk_bf16_f32 v117, v100, v101
	v_cvt_pk_bf16_f32 v118, v112, v113
	v_cvt_pk_bf16_f32 v119, v124, v125
	v_add_u32_e32 v109, v95, v90
	v_add_u32_e32 v8, 0x4000, v8
	ds_write_b128 v109, v[116:119] offset:32768
	v_add_u32_e32 v115, v110, v8
	v_lshrrev_b32_e32 v236, 1, v204
	v_and_b32_e32 v236, 0x30, v236
	v_xor_b32_e32 v236, v236, v115
	ds_read_b128 v[116:119], v236
	v_lshrrev_b32_e32 v237, 1, v204
	v_and_b32_e32 v237, 0x30, v237
	v_xor_b32_e32 v237, 16, v237
	v_xor_b32_e32 v237, v237, v115
	ds_read_b128 v[124:127], v237
	v_lshlrev_b32_e32 v76, 16, v20
	v_and_b32_e32 v77, 0xffff0000, v20
	v_lshlrev_b32_e32 v78, 16, v21
	s_waitcnt lgkmcnt(1)
	v_sub_f32_e32 v8, v96, v116
	v_mul_f32_e32 v8, 0x3fb8aa3b, v8
	v_exp_f32_e32 v96, v8
	v_sub_f32_e32 v8, v97, v117
	v_mul_f32_e32 v8, 0x3fb8aa3b, v8
	v_exp_f32_e32 v97, v8
	v_sub_f32_e32 v8, v98, v118
	v_mul_f32_e32 v8, 0x3fb8aa3b, v8
	v_exp_f32_e32 v98, v8
	v_sub_f32_e32 v8, v99, v119
	v_mul_f32_e32 v8, 0x3fb8aa3b, v8
	v_exp_f32_e32 v99, v8
	s_waitcnt lgkmcnt(0)
	v_sub_f32_e32 v8, v120, v124
	v_mul_f32_e32 v8, 0x3fb8aa3b, v8
	v_exp_f32_e32 v100, v8
	v_sub_f32_e32 v8, v121, v125
	v_mul_f32_e32 v8, 0x3fb8aa3b, v8
	v_exp_f32_e32 v101, v8
	v_sub_f32_e32 v8, v122, v126
	v_mul_f32_e32 v8, 0x3fb8aa3b, v8
	v_exp_f32_e32 v112, v8
	v_sub_f32_e32 v8, v123, v127
	v_mul_f32_e32 v8, 0x3fb8aa3b, v8
	v_exp_f32_e32 v113, v8
	v_and_b32_e32 v79, 0xffff0000, v21
	v_lshlrev_b32_e32 v80, 16, v22
	v_and_b32_e32 v81, 0xffff0000, v22
	v_lshlrev_b32_e32 v90, 16, v23
	v_and_b32_e32 v91, 0xffff0000, v23
	v_pk_mul_f32 v[96:97], v[96:97], v[76:77]
	v_pk_mul_f32 v[98:99], v[98:99], v[78:79]
	v_pk_mul_f32 v[100:101], v[100:101], v[80:81]
	v_pk_mul_f32 v[112:113], v[112:113], v[90:91]
	s_lshl_b32 s49, s51, 9
	v_cmp_gt_i32_e64 s[12:13], s44, v10
	v_cvt_pk_bf16_f32 v96, v96, v97
	v_cvt_pk_bf16_f32 v97, v98, v99
	v_cvt_pk_bf16_f32 v98, v100, v101
	v_cvt_pk_bf16_f32 v99, v112, v113
	v_lshl_add_u32 v111, v10, 2, 0
	ds_write_b128 v109, v[96:99] offset:41984
	s_and_saveexec_b64 s[58:59], s[12:13]
	s_cbranch_execz .LBB0_1317
	v_xor_b32_e32 v236, 48, v111
	ds_read_b32 v8, v236 offset:32256
	s_ashr_i32 s53, s52, 31
	s_lshl_b64 s[60:61], s[52:53], 15
	s_add_u32 s38, s0, s60
	s_addc_u32 s53, s1, s61
	s_waitcnt lgkmcnt(0)
	v_mul_f32_e32 v8, 0x3fb8aa3b, v8
	v_exp_f32_e32 v8, v8
	s_add_u32 s60, s38, s49
	s_addc_u32 s61, s53, 0
	v_lshl_add_u64 v[96:97], v[10:11], 2, s[60:61]
	global_store_dword v[96:97], v8, off

.LBB0_1325:
	v_mfma_f32_16x16x32_bf16 v[72:75], v[56:59], v[72:75], 0
	v_or_b32_e32 v93, 0x200, v105
	v_or_b32_e32 v118, 0x400, v105
	v_or_b32_e32 v119, 0x600, v105
	v_mfma_f32_16x16x32_bf16 v[68:71], v[56:59], v[68:71], 0
	v_or_b32_e32 v120, 0x800, v105
	s_waitcnt vmcnt(8)
	s_nop 1
	v_add_f32_e32 v132, v64, v72
	v_add_f32_e32 v73, v65, v73
	v_min_f32_e32 v72, 0, v132
	v_mul_f32_e64 v132, |v132|, s43
	v_mul_f32_e64 v133, |v73|, s43
	v_add_f32_e32 v134, v66, v74
	v_add_f32_e32 v75, v67, v75
	v_exp_f32_e32 v132, v132
	v_exp_f32_e32 v133, v133
	v_min_f32_e32 v74, 0, v134
	v_mul_f32_e64 v134, |v134|, s43
	v_mul_f32_e64 v135, |v75|, s43
	v_exp_f32_e32 v134, v134
	v_exp_f32_e32 v135, v135
	v_add_f32_e32 v132, 1.0, v132
	v_add_f32_e32 v133, 1.0, v133
	v_log_f32_e32 v132, v132
	v_log_f32_e32 v133, v133
	v_add_f32_e32 v134, 1.0, v134
	v_add_f32_e32 v135, 1.0, v135
	v_log_f32_e32 v134, v134
	v_log_f32_e32 v135, v135
	v_min_f32_e32 v73, 0, v73
	v_xor_b32_e32 v133, 0x80000000, v133
	v_xor_b32_e32 v132, 0x80000000, v132
	v_min_f32_e32 v75, 0, v75
	v_pk_fma_f32 v[72:73], v[132:133], s[46:47], v[72:73] op_sel_hi:[1,0,1]
	v_xor_b32_e32 v133, 0x80000000, v135
	v_xor_b32_e32 v132, 0x80000000, v134
	v_pk_fma_f32 v[74:75], v[132:133], s[46:47], v[74:75] op_sel_hi:[1,0,1]
	v_pk_mul_f32 v[72:73], v[72:73], s[50:51] op_sel_hi:[1,0]
	v_pk_mul_f32 v[74:75], v[74:75], s[50:51] op_sel_hi:[1,0]
	v_lshlrev_b32_e32 v237, 3, v204
	v_and_b32_e32 v237, 0x30, v237
	v_xor_b32_e32 v237, v237, v108
	ds_write_b128 v237, v[72:75]
	v_add_f32_e32 v72, v64, v68
	v_add_f32_e32 v69, v65, v69
	v_min_f32_e32 v68, 0, v72
	v_mul_f32_e64 v72, |v72|, s43
	v_mul_f32_e64 v73, |v69|, s43
	v_add_f32_e32 v74, v66, v70
	v_add_f32_e32 v71, v67, v71
	v_exp_f32_e32 v72, v72
	v_exp_f32_e32 v73, v73
	v_min_f32_e32 v70, 0, v74
	v_mul_f32_e64 v74, |v74|, s43
	v_mul_f32_e64 v75, |v71|, s43
	v_exp_f32_e32 v74, v74
	v_exp_f32_e32 v75, v75
	v_add_f32_e32 v72, 1.0, v72
	v_add_f32_e32 v73, 1.0, v73
	v_log_f32_e32 v72, v72
	v_log_f32_e32 v73, v73
	v_add_f32_e32 v74, 1.0, v74
	v_add_f32_e32 v75, 1.0, v75
	v_log_f32_e32 v74, v74
	v_log_f32_e32 v75, v75
	v_mfma_f32_16x16x32_bf16 v[52:55], v[56:59], v[52:55], 0
	v_min_f32_e32 v69, 0, v69
	v_xor_b32_e32 v73, 0x80000000, v73
	v_xor_b32_e32 v72, 0x80000000, v72
	v_mfma_f32_16x16x32_bf16 v[60:63], v[56:59], v[60:63], 0
	v_min_f32_e32 v71, 0, v71
	v_pk_fma_f32 v[68:69], v[72:73], s[46:47], v[68:69] op_sel_hi:[1,0,1]
	v_xor_b32_e32 v73, 0x80000000, v75
	v_xor_b32_e32 v72, 0x80000000, v74
	v_pk_fma_f32 v[70:71], v[72:73], s[46:47], v[70:71] op_sel_hi:[1,0,1]
	v_pk_mul_f32 v[68:69], v[68:69], s[50:51] op_sel_hi:[1,0]
	v_pk_mul_f32 v[70:71], v[70:71], s[50:51] op_sel_hi:[1,0]
	v_add_f32_e32 v56, v64, v52
	v_add_f32_e32 v53, v65, v53
	v_lshlrev_b32_e32 v236, 3, v204
	v_and_b32_e32 v236, 0x30, v236
	v_xor_b32_e32 v236, v236, v108
	ds_write_b128 v236, v[68:71] offset:8192
	v_add_f32_e32 v68, v64, v60
	v_add_f32_e32 v61, v65, v61
	v_min_f32_e32 v52, 0, v56
	v_mul_f32_e64 v56, |v56|, s43
	v_mul_f32_e64 v57, |v53|, s43
	v_add_f32_e32 v58, v66, v54
	v_add_f32_e32 v55, v67, v55
	v_min_f32_e32 v60, 0, v68
	v_mul_f32_e64 v68, |v68|, s43
	v_mul_f32_e64 v69, |v61|, s43
	v_add_f32_e32 v70, v66, v62
	v_add_f32_e32 v63, v67, v63
	v_exp_f32_e32 v56, v56
	v_exp_f32_e32 v57, v57
	v_min_f32_e32 v54, 0, v58
	v_mul_f32_e64 v58, |v58|, s43
	v_mul_f32_e64 v59, |v55|, s43
	v_exp_f32_e32 v68, v68
	v_exp_f32_e32 v69, v69
	v_min_f32_e32 v62, 0, v70
	v_mul_f32_e64 v70, |v70|, s43
	v_mul_f32_e64 v71, |v63|, s43
	v_exp_f32_e32 v58, v58
	v_exp_f32_e32 v59, v59
	v_exp_f32_e32 v70, v70
	v_exp_f32_e32 v71, v71
	v_add_f32_e32 v56, 1.0, v56
	v_add_f32_e32 v57, 1.0, v57
	v_add_f32_e32 v68, 1.0, v68
	v_add_f32_e32 v69, 1.0, v69
	v_log_f32_e32 v56, v56
	v_log_f32_e32 v57, v57
	v_add_f32_e32 v58, 1.0, v58
	v_add_f32_e32 v59, 1.0, v59
	v_log_f32_e32 v68, v68
	v_log_f32_e32 v69, v69
	v_add_f32_e32 v70, 1.0, v70
	v_add_f32_e32 v71, 1.0, v71
	v_log_f32_e32 v58, v58
	v_log_f32_e32 v59, v59
	v_log_f32_e32 v70, v70
	v_log_f32_e32 v71, v71
	v_min_f32_e32 v53, 0, v53
	v_xor_b32_e32 v57, 0x80000000, v57
	v_xor_b32_e32 v56, 0x80000000, v56
	v_min_f32_e32 v61, 0, v61
	v_xor_b32_e32 v69, 0x80000000, v69
	v_xor_b32_e32 v68, 0x80000000, v68
	v_min_f32_e32 v55, 0, v55
	v_pk_fma_f32 v[52:53], v[56:57], s[46:47], v[52:53] op_sel_hi:[1,0,1]
	v_xor_b32_e32 v57, 0x80000000, v59
	v_xor_b32_e32 v56, 0x80000000, v58
	v_min_f32_e32 v63, 0, v63
	v_pk_fma_f32 v[60:61], v[68:69], s[46:47], v[60:61] op_sel_hi:[1,0,1]
	v_xor_b32_e32 v69, 0x80000000, v71
	v_xor_b32_e32 v68, 0x80000000, v70
	v_pk_fma_f32 v[54:55], v[56:57], s[46:47], v[54:55] op_sel_hi:[1,0,1]
	v_or_b32_e32 v121, 0xa00, v105
	v_or_b32_e32 v122, 0xc00, v105
	v_or_b32_e32 v123, 0xe00, v105
	v_pk_fma_f32 v[62:63], v[68:69], s[46:47], v[62:63] op_sel_hi:[1,0,1]
	v_pk_mul_f32 v[54:55], v[54:55], s[50:51] op_sel_hi:[1,0]
	v_pk_mul_f32 v[52:53], v[52:53], s[50:51] op_sel_hi:[1,0]
	v_or_b32_e32 v124, 0x1000, v105
	v_or_b32_e32 v131, 0x1e00, v105
	v_pk_mul_f32 v[62:63], v[62:63], s[50:51] op_sel_hi:[1,0]
	v_pk_mul_f32 v[60:61], v[60:61], s[50:51] op_sel_hi:[1,0]
	v_lshlrev_b32_e32 v237, 3, v204
	v_and_b32_e32 v237, 0x30, v237
	v_xor_b32_e32 v237, v237, v108
	ds_write_b128 v237, v[52:55] offset:24576
	v_sub_u32_e32 v52, v104, v105
	v_sub_u32_e32 v53, v104, v93
	v_sub_u32_e32 v54, v104, v118
	v_sub_u32_e32 v55, v104, v119
	v_sub_u32_e32 v56, v104, v120
	v_sub_u32_e32 v57, v104, v121
	v_sub_u32_e32 v58, v104, v122
	v_sub_u32_e32 v59, v104, v123
	v_or_b32_e32 v125, 0x1200, v105
	v_or_b32_e32 v126, 0x1400, v105
	v_or_b32_e32 v127, 0x1600, v105
	v_or_b32_e32 v128, 0x1800, v105
	v_or_b32_e32 v129, 0x1a00, v105
	v_or_b32_e32 v130, 0x1c00, v105
	v_lshlrev_b32_e32 v236, 3, v204
	v_and_b32_e32 v236, 0x30, v236
	v_xor_b32_e32 v236, v236, v108
	ds_write_b128 v236, v[60:63] offset:16384
	s_waitcnt lgkmcnt(0)
	s_barrier
	v_xor_b32_e32 v237, 48, v52
	ds_read_b32 v52, v237 offset:32256
	v_xor_b32_e32 v236, 48, v53
	ds_read_b32 v53, v236 offset:32256
	v_xor_b32_e32 v237, 32, v54
	ds_read_b32 v54, v237 offset:32256
	v_xor_b32_e32 v236, 32, v55
	ds_read_b32 v55, v236 offset:32256
	v_xor_b32_e32 v237, 16, v56
	ds_read_b32 v56, v237 offset:32256
	v_xor_b32_e32 v236, 16, v57
	ds_read_b32 v57, v236 offset:32256
	ds_read_b32 v58, v58 offset:32256
	ds_read_b32 v59, v59 offset:32256
	v_sub_u32_e32 v60, v104, v124
	v_sub_u32_e32 v67, v104, v131
	s_waitcnt lgkmcnt(7)
	v_add_f32_e32 v68, 0, v52
	v_sub_u32_e32 v61, v104, v125
	v_sub_u32_e32 v62, v104, v126
	v_sub_u32_e32 v63, v104, v127
	v_sub_u32_e32 v64, v104, v128
	v_sub_u32_e32 v65, v104, v129
	v_sub_u32_e32 v66, v104, v130
	v_xor_b32_e32 v237, 48, v60
	ds_read_b32 v60, v237 offset:32256
	v_xor_b32_e32 v236, 48, v61
	ds_read_b32 v69, v236 offset:32256
	v_xor_b32_e32 v237, 32, v62
	ds_read_b32 v70, v237 offset:32256
	v_xor_b32_e32 v236, 32, v63
	ds_read_b32 v71, v236 offset:32256
	v_xor_b32_e32 v237, 16, v64
	ds_read_b32 v72, v237 offset:32256
	v_xor_b32_e32 v236, 16, v65
	ds_read_b32 v73, v236 offset:32256
	ds_read_b32 v74, v66 offset:32256
	ds_read_b32 v75, v67 offset:32256
	s_waitcnt lgkmcnt(14)
	v_add_f32_e32 v67, v68, v53
	s_waitcnt lgkmcnt(13)
	v_add_f32_e32 v66, v67, v54
	s_waitcnt lgkmcnt(12)
	v_add_f32_e32 v65, v66, v55
	s_waitcnt lgkmcnt(11)
	v_add_f32_e32 v64, v65, v56
	s_waitcnt lgkmcnt(10)
	v_add_f32_e32 v63, v64, v57
	s_waitcnt lgkmcnt(9)
	v_add_f32_e32 v62, v63, v58
	s_waitcnt lgkmcnt(8)
	v_add_f32_e32 v61, v62, v59
	s_waitcnt lgkmcnt(7)
	v_add_f32_e32 v60, v61, v60
	s_waitcnt lgkmcnt(6)
	v_add_f32_e32 v59, v60, v69
	s_waitcnt lgkmcnt(5)
	v_add_f32_e32 v58, v59, v70
	s_waitcnt lgkmcnt(4)
	v_add_f32_e32 v57, v58, v71
	s_waitcnt lgkmcnt(3)
	v_add_f32_e32 v55, v57, v72
	s_waitcnt lgkmcnt(2)
	v_add_f32_e32 v54, v55, v73
	s_waitcnt lgkmcnt(1)
	v_add_f32_e32 v53, v54, v74
	s_waitcnt lgkmcnt(0)
	v_add_f32_e32 v52, v53, v75
	v_mov_b32_e32 v56, 0
	ds_write_b32 v107, v52
	s_waitcnt lgkmcnt(0)
	s_barrier
	s_and_saveexec_b64 s[52:53], s[10:11]
	s_cbranch_execnz .LBB0_1368
	s_or_b64 exec, exec, s[52:53]
	s_and_saveexec_b64 s[10:11], s[14:15]
	s_cbranch_execnz .LBB0_1369

.LBB0_1329:
	s_or_b64 exec, exec, s[10:11]
	v_sub_u32_e32 v69, 0, v105
	v_sub_u32_e32 v70, 0, v93
	v_add_f32_e32 v68, v68, v56
	v_add_u32_e32 v69, v104, v69
	v_sub_u32_e32 v71, 0, v118
	v_xor_b32_e32 v237, 48, v69
	ds_write_b32 v237, v68 offset:32256
	v_add_f32_e32 v67, v67, v56
	v_add_u32_e32 v68, v104, v70
	v_sub_u32_e32 v72, 0, v119
	v_xor_b32_e32 v236, 48, v68
	ds_write_b32 v236, v67 offset:32256
	v_add_f32_e32 v66, v66, v56
	v_add_u32_e32 v67, v104, v71
	v_sub_u32_e32 v73, 0, v120
	v_xor_b32_e32 v237, 32, v67
	ds_write_b32 v237, v66 offset:32256
	v_add_f32_e32 v65, v65, v56
	v_add_u32_e32 v66, v104, v72
	v_sub_u32_e32 v74, 0, v121
	v_xor_b32_e32 v236, 32, v66
	ds_write_b32 v236, v65 offset:32256
	v_add_f32_e32 v64, v64, v56
	v_add_u32_e32 v65, v104, v73
	v_sub_u32_e32 v75, 0, v122
	v_xor_b32_e32 v237, 16, v65
	ds_write_b32 v237, v64 offset:32256
	v_add_f32_e32 v63, v63, v56
	v_add_u32_e32 v64, v104, v74
	v_sub_u32_e32 v93, 0, v123
	v_xor_b32_e32 v236, 16, v64
	ds_write_b32 v236, v63 offset:32256
	v_add_f32_e32 v62, v62, v56
	v_add_u32_e32 v63, v104, v75
	v_sub_u32_e32 v105, 0, v124
	ds_write_b32 v63, v62 offset:32256
	v_add_f32_e32 v61, v61, v56
	v_add_u32_e32 v62, v104, v93
	v_sub_u32_e32 v106, 0, v125
	ds_write_b32 v62, v61 offset:32256
	v_add_f32_e32 v60, v60, v56
	v_add_u32_e32 v61, v104, v105
	v_sub_u32_e32 v107, 0, v126
	v_xor_b32_e32 v237, 48, v61
	ds_write_b32 v237, v60 offset:32256
	v_add_f32_e32 v59, v59, v56
	v_add_u32_e32 v60, v104, v106
	v_sub_u32_e32 v108, 0, v127
	v_xor_b32_e32 v236, 48, v60
	ds_write_b32 v236, v59 offset:32256
	v_add_f32_e32 v58, v58, v56
	v_add_u32_e32 v59, v104, v107
	v_sub_u32_e32 v118, 0, v128
	v_xor_b32_e32 v237, 32, v59
	ds_write_b32 v237, v58 offset:32256
	v_add_f32_e32 v57, v57, v56
	v_add_u32_e32 v58, v104, v108
	v_sub_u32_e32 v119, 0, v129
	v_xor_b32_e32 v236, 32, v58
	ds_write_b32 v236, v57 offset:32256
	v_add_f32_e32 v55, v55, v56
	v_add_u32_e32 v57, v104, v118
	v_sub_u32_e32 v120, 0, v130
	v_xor_b32_e32 v237, 16, v57
	ds_write_b32 v237, v55 offset:32256
	v_add_f32_e32 v54, v54, v56
	v_add_u32_e32 v55, v104, v119
	v_sub_u32_e32 v121, 0, v131
	v_xor_b32_e32 v236, 16, v55
	ds_write_b32 v236, v54 offset:32256
	v_add_f32_e32 v53, v53, v56
	v_add_u32_e32 v54, v104, v120
	ds_write_b32 v54, v53 offset:32256
	v_add_f32_e32 v52, v52, v56
	v_add_u32_e32 v53, v104, v121
	ds_write_b32 v53, v52 offset:32256
	s_waitcnt lgkmcnt(0)
	s_barrier
	v_lshrrev_b32_e32 v237, 1, v204
	v_and_b32_e32 v237, 0x30, v237
	v_xor_b32_e32 v237, v237, v114
	ds_read_b128 v[52:55], v237
	ds_read_b128 v[56:59], v110
	v_xor_b32_e32 v236, 16, v110
	ds_read_b128 v[60:63], v236
	v_lshrrev_b32_e32 v237, 1, v204
	v_and_b32_e32 v237, 0x30, v237
	v_xor_b32_e32 v237, 16, v237
	v_xor_b32_e32 v237, v237, v114
	ds_read_b128 v[64:67], v237
	s_waitcnt lgkmcnt(2)
	v_sub_f32_e32 v52, v56, v52
	v_sub_f32_e32 v53, v57, v53
	v_sub_f32_e32 v54, v58, v54
	v_sub_f32_e32 v55, v59, v55
	s_waitcnt lgkmcnt(0)
	v_sub_f32_e32 v64, v60, v64
	v_sub_f32_e32 v65, v61, v65
	v_sub_f32_e32 v66, v62, v66
	v_sub_f32_e32 v67, v63, v67
	v_mul_f32_e32 v52, 0x3fb8aa3b, v52
	v_mul_f32_e32 v53, 0x3fb8aa3b, v53
	v_mul_f32_e32 v54, 0x3fb8aa3b, v54
	v_mul_f32_e32 v55, 0x3fb8aa3b, v55
	v_mul_f32_e32 v64, 0x3fb8aa3b, v64
	v_mul_f32_e32 v65, 0x3fb8aa3b, v65
	v_mul_f32_e32 v66, 0x3fb8aa3b, v66
	v_mul_f32_e32 v67, 0x3fb8aa3b, v67
	v_exp_f32_e32 v52, v52
	v_exp_f32_e32 v53, v53
	v_exp_f32_e32 v54, v54
	v_exp_f32_e32 v55, v55
	v_exp_f32_e32 v64, v64
	v_exp_f32_e32 v65, v65
	v_exp_f32_e32 v66, v66
	v_exp_f32_e32 v67, v67
	v_pk_mul_f32 v[52:53], v[52:53], v[82:83]
	v_pk_mul_f32 v[54:55], v[54:55], v[84:85]
	v_pk_mul_f32 v[64:65], v[64:65], v[86:87]
	v_pk_mul_f32 v[66:67], v[66:67], v[88:89]
	v_cvt_pk_bf16_f32 v52, v52, v53
	v_cvt_pk_bf16_f32 v53, v54, v55
	v_cvt_pk_bf16_f32 v54, v64, v65
	v_cvt_pk_bf16_f32 v55, v66, v67
	ds_write_b128 v109, v[52:55] offset:32768
	v_lshrrev_b32_e32 v236, 1, v204
	v_and_b32_e32 v236, 0x30, v236
	v_xor_b32_e32 v236, v236, v115
	ds_read_b128 v[52:55], v236
	v_lshrrev_b32_e32 v237, 1, v204
	v_and_b32_e32 v237, 0x30, v237
	v_xor_b32_e32 v237, 16, v237
	v_xor_b32_e32 v237, v237, v115
	ds_read_b128 v[64:67], v237
	s_waitcnt lgkmcnt(1)
	v_sub_f32_e32 v52, v56, v52
	v_sub_f32_e32 v53, v57, v53
	v_sub_f32_e32 v54, v58, v54
	v_sub_f32_e32 v55, v59, v55
	s_waitcnt lgkmcnt(0)
	v_sub_f32_e32 v56, v60, v64
	v_sub_f32_e32 v57, v61, v65
	v_sub_f32_e32 v58, v62, v66
	v_sub_f32_e32 v59, v63, v67
	v_mul_f32_e32 v52, 0x3fb8aa3b, v52
	v_mul_f32_e32 v53, 0x3fb8aa3b, v53
	v_mul_f32_e32 v54, 0x3fb8aa3b, v54
	v_mul_f32_e32 v55, 0x3fb8aa3b, v55
	v_mul_f32_e32 v56, 0x3fb8aa3b, v56
	v_mul_f32_e32 v57, 0x3fb8aa3b, v57
	v_mul_f32_e32 v58, 0x3fb8aa3b, v58
	v_mul_f32_e32 v59, 0x3fb8aa3b, v59
	v_exp_f32_e32 v52, v52
	v_exp_f32_e32 v53, v53
	v_exp_f32_e32 v54, v54
	v_exp_f32_e32 v55, v55
	v_exp_f32_e32 v56, v56
	v_exp_f32_e32 v57, v57
	v_exp_f32_e32 v58, v58
	v_exp_f32_e32 v59, v59
	v_pk_mul_f32 v[52:53], v[52:53], v[76:77]
	v_pk_mul_f32 v[54:55], v[54:55], v[78:79]
	v_pk_mul_f32 v[56:57], v[56:57], v[80:81]
	v_pk_mul_f32 v[58:59], v[58:59], v[90:91]
	v_cvt_pk_bf16_f32 v52, v52, v53
	v_cvt_pk_bf16_f32 v53, v54, v55
	v_cvt_pk_bf16_f32 v54, v56, v57
	v_cvt_pk_bf16_f32 v55, v58, v59
	ds_write_b128 v109, v[52:55] offset:41984
	s_and_saveexec_b64 s[10:11], s[12:13]
	s_cbranch_execz .LBB0_1331
	v_lshrrev_b32_e32 v236, 4, v204
	v_and_b32_e32 v236, 0x30, v236
	v_xor_b32_e32 v236, v236, v111
	ds_read_b32 v52, v236
	s_ashr_i32 s59, s58, 31
	s_lshl_b64 s[12:13], s[58:59], 15
	s_add_u32 s12, s0, s12
	s_addc_u32 s13, s1, s13
	s_waitcnt lgkmcnt(0)
	v_mul_f32_e32 v52, 0x3fb8aa3b, v52
	v_exp_f32_e32 v52, v52
	s_add_u32 s12, s12, s49
	s_addc_u32 s13, s13, 0
	v_lshl_add_u64 v[10:11], v[10:11], 2, s[12:13]
	global_store_dword v[10:11], v52, off

.LBB0_1346:
	v_lshlrev_b32_e32 v86, 2, v10
	v_and_b32_e32 v87, 0x1fc, v86
	v_add_u32_e32 v104, 0, v87
	v_add_u32_e32 v107, s92, v86
	v_add_u32_e32 v106, s92, v87
	s_nop 0
	v_mfma_f32_16x16x32_bf16 v[86:89], v[76:79], v[72:75], 0
	v_lshlrev_b32_e32 v84, 9, v92
	v_and_b32_e32 v85, 0xffffffc0, v10
	v_add3_u32 v85, 0, v84, v85
	v_add_u32_e32 v108, v85, v8
	v_ashrrev_i32_e32 v84, 7, v10
	s_nop 0
	s_nop 1
	v_add_f32_e32 v90, v80, v86
	v_add_f32_e32 v87, v81, v87
	v_min_f32_e32 v86, 0, v90
	v_mul_f32_e64 v90, |v90|, s43
	v_mul_f32_e64 v91, |v87|, s43
	v_add_f32_e32 v95, v82, v88
	v_add_f32_e32 v89, v83, v89
	v_exp_f32_e32 v90, v90
	v_exp_f32_e32 v91, v91
	v_min_f32_e32 v88, 0, v95
	v_mul_f32_e64 v95, |v95|, s43
	v_mul_f32_e64 v96, |v89|, s43
	v_exp_f32_e32 v95, v95
	v_exp_f32_e32 v96, v96
	v_add_f32_e32 v90, 1.0, v90
	v_add_f32_e32 v91, 1.0, v91
	v_log_f32_e32 v90, v90
	v_log_f32_e32 v91, v91
	v_add_f32_e32 v95, 1.0, v95
	v_add_f32_e32 v96, 1.0, v96
	v_log_f32_e32 v95, v95
	v_log_f32_e32 v96, v96
	v_min_f32_e32 v87, 0, v87
	v_xor_b32_e32 v91, 0x80000000, v91
	v_xor_b32_e32 v90, 0x80000000, v90
	v_min_f32_e32 v89, 0, v89
	v_pk_fma_f32 v[86:87], v[90:91], s[46:47], v[86:87] op_sel_hi:[1,0,1]
	v_xor_b32_e32 v91, 0x80000000, v96
	v_xor_b32_e32 v90, 0x80000000, v95
	v_pk_fma_f32 v[88:89], v[90:91], s[46:47], v[88:89] op_sel_hi:[1,0,1]
	v_pk_mul_f32 v[86:87], v[86:87], s[50:51] op_sel_hi:[1,0]
	v_pk_mul_f32 v[88:89], v[88:89], s[50:51] op_sel_hi:[1,0]
	v_lshlrev_b32_e32 v237, 3, v204
	v_and_b32_e32 v237, 0x30, v237
	v_xor_b32_e32 v237, v237, v108
	ds_write_b128 v237, v[86:89]
	v_mfma_f32_16x16x32_bf16 v[86:89], v[76:79], v[68:71], 0
	v_lshlrev_b32_e32 v105, 13, v84
	v_cmp_lt_i32_e64 s[10:11], 0, v84
	v_mov_b32_e32 v117, 0
	s_nop 4
	v_add_f32_e32 v85, v81, v87
	v_mul_f32_e64 v87, |v85|, s43
	v_exp_f32_e32 v90, v87
	v_add_f32_e32 v8, v80, v86
	v_min_f32_e32 v87, 0, v85
	v_min_f32_e32 v86, 0, v8
	v_add_f32_e32 v85, 1.0, v90
	v_add_f32_e32 v90, v82, v88
	v_mul_f32_e64 v8, |v8|, s43
	v_min_f32_e32 v88, 0, v90
	v_mul_f32_e64 v90, |v90|, s43
	v_add_f32_e32 v89, v83, v89
	v_exp_f32_e32 v8, v8
	v_exp_f32_e32 v90, v90
	v_mul_f32_e64 v91, |v89|, s43
	v_exp_f32_e32 v91, v91
	v_add_f32_e32 v8, 1.0, v8
	v_add_f32_e32 v90, 1.0, v90
	v_log_f32_e32 v8, v8
	v_log_f32_e32 v85, v85
	v_log_f32_e32 v95, v90
	v_add_f32_e32 v90, 1.0, v91
	v_log_f32_e32 v96, v90
	v_xor_b32_e32 v91, 0x80000000, v85
	v_xor_b32_e32 v90, 0x80000000, v8
	v_min_f32_e32 v89, 0, v89
	v_pk_fma_f32 v[86:87], v[90:91], s[46:47], v[86:87] op_sel_hi:[1,0,1]
	v_xor_b32_e32 v91, 0x80000000, v96
	v_xor_b32_e32 v90, 0x80000000, v95
	v_pk_fma_f32 v[88:89], v[90:91], s[46:47], v[88:89] op_sel_hi:[1,0,1]
	v_pk_mul_f32 v[86:87], v[86:87], s[50:51] op_sel_hi:[1,0]
	v_pk_mul_f32 v[88:89], v[88:89], s[50:51] op_sel_hi:[1,0]
	v_lshlrev_b32_e32 v236, 3, v204
	v_and_b32_e32 v236, 0x30, v236
	v_xor_b32_e32 v236, v236, v108
	ds_write_b128 v236, v[86:89] offset:8192
	v_mfma_f32_16x16x32_bf16 v[86:89], v[76:79], v[60:63], 0
	v_mfma_f32_16x16x32_bf16 v[76:79], v[76:79], v[52:55], 0
	s_nop 6
	v_add_f32_e32 v85, v81, v87
	v_mul_f32_e64 v87, |v85|, s43
	v_exp_f32_e32 v90, v87
	v_add_f32_e32 v8, v80, v86
	v_min_f32_e32 v86, 0, v8
	v_mul_f32_e64 v8, |v8|, s43
	v_exp_f32_e32 v8, v8
	v_min_f32_e32 v87, 0, v85
	v_add_f32_e32 v85, 1.0, v90
	v_add_f32_e32 v90, v82, v88
	v_min_f32_e32 v88, 0, v90
	v_mul_f32_e64 v90, |v90|, s43
	v_add_f32_e32 v89, v83, v89
	v_exp_f32_e32 v90, v90
	v_mul_f32_e64 v91, |v89|, s43
	v_add_f32_e32 v8, 1.0, v8
	v_exp_f32_e32 v91, v91
	v_log_f32_e32 v8, v8
	v_add_f32_e32 v90, 1.0, v90
	v_log_f32_e32 v95, v90
	v_add_f32_e32 v90, 1.0, v91
	v_log_f32_e32 v96, v90
	v_xor_b32_e32 v90, 0x80000000, v8
	v_add_f32_e32 v8, v80, v76
	v_add_f32_e32 v77, v81, v77
	v_add_f32_e32 v81, v82, v78
	v_min_f32_e32 v76, 0, v8
	v_mul_f32_e64 v8, |v8|, s43
	v_mul_f32_e64 v80, |v77|, s43
	v_min_f32_e32 v78, 0, v81
	v_mul_f32_e64 v81, |v81|, s43
	v_add_f32_e32 v79, v83, v79
	v_exp_f32_e32 v8, v8
	v_exp_f32_e32 v80, v80
	v_exp_f32_e32 v81, v81
	v_mul_f32_e64 v82, |v79|, s43
	v_exp_f32_e32 v82, v82
	v_add_f32_e32 v8, 1.0, v8
	v_add_f32_e32 v80, 1.0, v80
	v_add_f32_e32 v81, 1.0, v81
	v_log_f32_e32 v85, v85
	v_log_f32_e32 v8, v8
	v_log_f32_e32 v80, v80
	v_log_f32_e32 v83, v81
	v_add_f32_e32 v81, 1.0, v82
	v_log_f32_e32 v82, v81
	v_xor_b32_e32 v91, 0x80000000, v85
	v_min_f32_e32 v77, 0, v77
	v_xor_b32_e32 v81, 0x80000000, v80
	v_xor_b32_e32 v80, 0x80000000, v8
	v_min_f32_e32 v89, 0, v89
	v_pk_fma_f32 v[86:87], v[90:91], s[46:47], v[86:87] op_sel_hi:[1,0,1]
	v_xor_b32_e32 v91, 0x80000000, v96
	v_xor_b32_e32 v90, 0x80000000, v95
	v_min_f32_e32 v79, 0, v79
	v_pk_fma_f32 v[76:77], v[80:81], s[46:47], v[76:77] op_sel_hi:[1,0,1]
	v_xor_b32_e32 v81, 0x80000000, v82
	v_xor_b32_e32 v80, 0x80000000, v83
	v_pk_fma_f32 v[88:89], v[90:91], s[46:47], v[88:89] op_sel_hi:[1,0,1]
	v_pk_fma_f32 v[78:79], v[80:81], s[46:47], v[78:79] op_sel_hi:[1,0,1]
	v_pk_mul_f32 v[88:89], v[88:89], s[50:51] op_sel_hi:[1,0]
	v_pk_mul_f32 v[86:87], v[86:87], s[50:51] op_sel_hi:[1,0]
	v_pk_mul_f32 v[78:79], v[78:79], s[50:51] op_sel_hi:[1,0]
	v_pk_mul_f32 v[76:77], v[76:77], s[50:51] op_sel_hi:[1,0]
	v_add_u32_e32 v8, v104, v105
	v_lshlrev_b32_e32 v237, 3, v204
	v_and_b32_e32 v237, 0x30, v237
	v_xor_b32_e32 v237, v237, v108
	ds_write_b128 v237, v[86:89] offset:16384
	v_lshlrev_b32_e32 v236, 3, v204
	v_and_b32_e32 v236, 0x30, v236
	v_xor_b32_e32 v236, v236, v108
	ds_write_b128 v236, v[76:79] offset:24576
	s_waitcnt lgkmcnt(0)
	s_barrier
	ds_read2st64_b32 v[76:77], v8 offset1:2
	v_xor_b32_e32 v237, 16, v8
	ds_read2st64_b32 v[78:79], v237 offset0:4 offset1:6
	v_xor_b32_e32 v236, 32, v8
	ds_read2st64_b32 v[80:81], v236 offset0:8 offset1:10
	v_xor_b32_e32 v237, 48, v8
	ds_read2st64_b32 v[82:83], v237 offset0:12 offset1:14
	ds_read2st64_b32 v[86:87], v8 offset0:16 offset1:18
	v_xor_b32_e32 v236, 16, v8
	ds_read2st64_b32 v[88:89], v236 offset0:20 offset1:22
	v_xor_b32_e32 v237, 32, v8
	ds_read2st64_b32 v[90:91], v237 offset0:24 offset1:26
	v_xor_b32_e32 v236, 48, v8
	ds_read2st64_b32 v[118:119], v236 offset0:28 offset1:30
	s_waitcnt lgkmcnt(7)
	v_add_f32_e32 v115, 0, v76
	v_add_f32_e32 v116, v115, v77
	s_waitcnt lgkmcnt(6)
	v_add_f32_e32 v113, v116, v78
	v_add_f32_e32 v114, v113, v79
	s_waitcnt lgkmcnt(5)
	v_add_f32_e32 v111, v114, v80
	v_add_f32_e32 v112, v111, v81
	s_waitcnt lgkmcnt(4)
	v_add_f32_e32 v101, v112, v82
	v_add_f32_e32 v109, v101, v83
	s_waitcnt lgkmcnt(3)
	v_add_f32_e32 v99, v109, v86
	v_add_f32_e32 v100, v99, v87
	s_waitcnt lgkmcnt(2)
	v_add_f32_e32 v97, v100, v88
	v_add_f32_e32 v98, v97, v89
	s_waitcnt lgkmcnt(1)
	v_add_f32_e32 v95, v98, v90
	v_add_f32_e32 v96, v95, v91
	s_waitcnt lgkmcnt(0)
	v_add_f32_e32 v90, v96, v118
	v_add_f32_e32 v91, v90, v119
	ds_write_b32 v107, v91
	s_waitcnt lgkmcnt(0)
	s_barrier
	s_and_saveexec_b64 s[12:13], s[10:11]
	s_cbranch_execnz .LBB0_1370
	s_or_b64 exec, exec, s[12:13]
	v_cmp_lt_i32_e64 s[14:15], 1, v84
	s_and_saveexec_b64 s[12:13], s[14:15]
	s_cbranch_execnz .LBB0_1371

.LBB0_1350:
	s_or_b64 exec, exec, s[12:13]
	v_lshlrev_b32_e32 v110, 3, v10
	v_and_b32_e32 v120, 0x78, v110
	v_ashrrev_i32_e32 v128, 4, v10
	v_add_f32_e32 v115, v115, v117
	v_add_f32_e32 v116, v116, v117
	v_add_f32_e32 v113, v113, v117
	v_add_f32_e32 v114, v114, v117
	v_add_f32_e32 v111, v111, v117
	v_add_f32_e32 v112, v112, v117
	v_add_f32_e32 v101, v101, v117
	v_add_f32_e32 v109, v109, v117
	v_add_f32_e32 v99, v99, v117
	v_add_f32_e32 v100, v100, v117
	v_add_f32_e32 v97, v97, v117
	v_add_f32_e32 v98, v98, v117
	v_add_f32_e32 v95, v95, v117
	v_add_f32_e32 v96, v96, v117
	v_add_f32_e32 v90, v90, v117
	v_add_f32_e32 v91, v91, v117
	v_lshl_add_u32 v110, v120, 2, 0
	ds_write2st64_b32 v8, v115, v116 offset1:2
	v_xor_b32_e32 v237, 16, v8
	ds_write2st64_b32 v237, v113, v114 offset0:4 offset1:6
	v_xor_b32_e32 v236, 32, v8
	ds_write2st64_b32 v236, v111, v112 offset0:8 offset1:10
	v_xor_b32_e32 v237, 48, v8
	ds_write2st64_b32 v237, v101, v109 offset0:12 offset1:14
	ds_write2st64_b32 v8, v99, v100 offset0:16 offset1:18
	v_xor_b32_e32 v236, 16, v8
	ds_write2st64_b32 v236, v97, v98 offset0:20 offset1:22
	v_xor_b32_e32 v237, 32, v8
	ds_write2st64_b32 v237, v95, v96 offset0:24 offset1:26
	v_xor_b32_e32 v236, 48, v8
	ds_write2st64_b32 v236, v90, v91 offset0:28 offset1:30
	v_lshlrev_b32_e32 v8, 9, v128
	v_add_u32_e32 v114, v110, v8
	s_waitcnt lgkmcnt(0)
	s_barrier
	v_xor_b32_e32 v237, 48, v110
	ds_read_b128 v[96:99], v237 offset:32256
	v_lshrrev_b32_e32 v236, 1, v204
	v_and_b32_e32 v236, 0x30, v236
	v_xor_b32_e32 v236, v236, v114
	ds_read_b128 v[116:119], v236
	v_lshlrev_b32_e32 v90, 1, v120
	v_xor_b32_e32 v237, 32, v110
	ds_read_b128 v[120:123], v237 offset:32256
	v_lshrrev_b32_e32 v236, 1, v204
	v_and_b32_e32 v236, 0x30, v236
	v_xor_b32_e32 v236, 16, v236
	v_xor_b32_e32 v236, v236, v114
	ds_read_b128 v[124:127], v236
	v_sub_u32_e32 v95, v110, v90
	v_lshlrev_b32_e32 v82, 16, v44
	s_waitcnt lgkmcnt(2)
	v_sub_f32_e32 v90, v96, v116
	v_sub_f32_e32 v91, v97, v117
	s_waitcnt lgkmcnt(0)
	v_sub_f32_e32 v109, v120, v124
	v_mul_f32_e32 v109, 0x3fb8aa3b, v109
	v_exp_f32_e32 v112, v109
	v_sub_f32_e32 v109, v121, v125
	v_mul_f32_e32 v109, 0x3fb8aa3b, v109
	v_exp_f32_e32 v113, v109
	v_sub_f32_e32 v109, v122, v126
	v_mul_f32_e32 v109, 0x3fb8aa3b, v109
	v_mul_f32_e32 v90, 0x3fb8aa3b, v90
	v_mul_f32_e32 v91, 0x3fb8aa3b, v91
	v_sub_f32_e32 v100, v98, v118
	v_sub_f32_e32 v101, v99, v119
	v_exp_f32_e32 v116, v109
	v_sub_f32_e32 v109, v123, v127
	v_exp_f32_e32 v90, v90
	v_exp_f32_e32 v91, v91
	v_mul_f32_e32 v100, 0x3fb8aa3b, v100
	v_mul_f32_e32 v101, 0x3fb8aa3b, v101
	v_mul_f32_e32 v109, 0x3fb8aa3b, v109
	v_exp_f32_e32 v100, v100
	v_exp_f32_e32 v101, v101
	v_exp_f32_e32 v117, v109
	v_and_b32_e32 v83, 0xffff0000, v44
	v_lshlrev_b32_e32 v84, 16, v45
	v_and_b32_e32 v85, 0xffff0000, v45
	v_lshlrev_b32_e32 v86, 16, v46
	v_and_b32_e32 v87, 0xffff0000, v46
	v_lshlrev_b32_e32 v88, 16, v47
	v_and_b32_e32 v89, 0xffff0000, v47
	v_pk_mul_f32 v[90:91], v[90:91], v[82:83]
	v_pk_mul_f32 v[100:101], v[100:101], v[84:85]
	v_pk_mul_f32 v[112:113], v[112:113], v[86:87]
	v_pk_mul_f32 v[124:125], v[116:117], v[88:89]
	v_cvt_pk_bf16_f32 v116, v90, v91
	v_mul_lo_u32 v90, v128, s45
	v_cvt_pk_bf16_f32 v117, v100, v101
	v_cvt_pk_bf16_f32 v118, v112, v113
	v_cvt_pk_bf16_f32 v119, v124, v125
	v_add_u32_e32 v109, v95, v90
	v_add_u32_e32 v8, 0x4000, v8
	ds_write_b128 v109, v[116:119] offset:32768
	v_add_u32_e32 v115, v110, v8
	v_lshrrev_b32_e32 v237, 1, v204
	v_and_b32_e32 v237, 0x30, v237
	v_xor_b32_e32 v237, v237, v115
	ds_read_b128 v[116:119], v237
	v_lshrrev_b32_e32 v236, 1, v204
	v_and_b32_e32 v236, 0x30, v236
	v_xor_b32_e32 v236, 16, v236
	v_xor_b32_e32 v236, v236, v115
	ds_read_b128 v[124:127], v236
	v_lshlrev_b32_e32 v76, 16, v48
	v_and_b32_e32 v77, 0xffff0000, v48
	v_lshlrev_b32_e32 v78, 16, v49
	s_waitcnt lgkmcnt(1)
	v_sub_f32_e32 v8, v96, v116
	v_mul_f32_e32 v8, 0x3fb8aa3b, v8
	v_exp_f32_e32 v96, v8
	v_sub_f32_e32 v8, v97, v117
	v_mul_f32_e32 v8, 0x3fb8aa3b, v8
	v_exp_f32_e32 v97, v8
	v_sub_f32_e32 v8, v98, v118
	v_mul_f32_e32 v8, 0x3fb8aa3b, v8
	v_exp_f32_e32 v98, v8
	v_sub_f32_e32 v8, v99, v119
	v_mul_f32_e32 v8, 0x3fb8aa3b, v8
	v_exp_f32_e32 v99, v8
	s_waitcnt lgkmcnt(0)
	v_sub_f32_e32 v8, v120, v124
	v_mul_f32_e32 v8, 0x3fb8aa3b, v8
	v_exp_f32_e32 v100, v8
	v_sub_f32_e32 v8, v121, v125
	v_mul_f32_e32 v8, 0x3fb8aa3b, v8
	v_exp_f32_e32 v101, v8
	v_sub_f32_e32 v8, v122, v126
	v_mul_f32_e32 v8, 0x3fb8aa3b, v8
	v_exp_f32_e32 v112, v8
	v_sub_f32_e32 v8, v123, v127
	v_mul_f32_e32 v8, 0x3fb8aa3b, v8
	v_exp_f32_e32 v113, v8
	v_and_b32_e32 v79, 0xffff0000, v49
	v_lshlrev_b32_e32 v80, 16, v50
	v_and_b32_e32 v81, 0xffff0000, v50
	v_lshlrev_b32_e32 v90, 16, v51
	v_and_b32_e32 v91, 0xffff0000, v51
	v_pk_mul_f32 v[96:97], v[96:97], v[76:77]
	v_pk_mul_f32 v[98:99], v[98:99], v[78:79]
	v_pk_mul_f32 v[100:101], v[100:101], v[80:81]
	v_pk_mul_f32 v[112:113], v[112:113], v[90:91]
	s_lshl_b32 s2, s49, 9
	v_cmp_gt_i32_e64 s[12:13], s44, v10
	v_cvt_pk_bf16_f32 v96, v96, v97
	v_cvt_pk_bf16_f32 v97, v98, v99
	v_cvt_pk_bf16_f32 v98, v100, v101
	v_cvt_pk_bf16_f32 v99, v112, v113
	v_lshl_add_u32 v112, v10, 2, 0
	ds_write_b128 v109, v[96:99] offset:41984
	s_and_saveexec_b64 s[58:59], s[12:13]
	s_cbranch_execz .LBB0_1352
	v_xor_b32_e32 v237, 48, v112
	ds_read_b32 v8, v237 offset:32256
	s_ashr_i32 s53, s52, 31
	s_lshl_b64 s[60:61], s[52:53], 15
	s_add_u32 s38, s0, s60
	s_addc_u32 s51, s1, s61
	s_waitcnt lgkmcnt(0)
	v_mul_f32_e32 v8, 0x3fb8aa3b, v8
	v_exp_f32_e32 v8, v8
	s_add_u32 s60, s38, s2
	s_addc_u32 s61, s51, 0
	v_lshl_add_u64 v[96:97], v[10:11], 2, s[60:61]
	global_store_dword v[96:97], v8, off

.LBB0_1360:
	v_mfma_f32_16x16x32_bf16 v[72:75], v[56:59], v[72:75], 0
	v_or_b32_e32 v93, 0x200, v105
	v_or_b32_e32 v118, 0x400, v105
	v_or_b32_e32 v119, 0x600, v105
	v_mfma_f32_16x16x32_bf16 v[68:71], v[56:59], v[68:71], 0
	v_or_b32_e32 v120, 0x800, v105
	s_waitcnt vmcnt(8)
	s_nop 1
	v_add_f32_e32 v132, v64, v72
	v_add_f32_e32 v73, v65, v73
	v_min_f32_e32 v72, 0, v132
	v_mul_f32_e64 v132, |v132|, s43
	v_mul_f32_e64 v133, |v73|, s43
	v_add_f32_e32 v134, v66, v74
	v_add_f32_e32 v75, v67, v75
	v_exp_f32_e32 v132, v132
	v_exp_f32_e32 v133, v133
	v_min_f32_e32 v74, 0, v134
	v_mul_f32_e64 v134, |v134|, s43
	v_mul_f32_e64 v135, |v75|, s43
	v_exp_f32_e32 v134, v134
	v_exp_f32_e32 v135, v135
	v_add_f32_e32 v132, 1.0, v132
	v_add_f32_e32 v133, 1.0, v133
	v_log_f32_e32 v132, v132
	v_log_f32_e32 v133, v133
	v_add_f32_e32 v134, 1.0, v134
	v_add_f32_e32 v135, 1.0, v135
	v_log_f32_e32 v134, v134
	v_log_f32_e32 v135, v135
	v_min_f32_e32 v73, 0, v73
	v_xor_b32_e32 v133, 0x80000000, v133
	v_xor_b32_e32 v132, 0x80000000, v132
	v_min_f32_e32 v75, 0, v75
	v_pk_fma_f32 v[72:73], v[132:133], s[46:47], v[72:73] op_sel_hi:[1,0,1]
	v_xor_b32_e32 v133, 0x80000000, v135
	v_xor_b32_e32 v132, 0x80000000, v134
	v_pk_fma_f32 v[74:75], v[132:133], s[46:47], v[74:75] op_sel_hi:[1,0,1]
	v_pk_mul_f32 v[72:73], v[72:73], s[50:51] op_sel_hi:[1,0]
	v_pk_mul_f32 v[74:75], v[74:75], s[50:51] op_sel_hi:[1,0]
	v_lshlrev_b32_e32 v236, 3, v204
	v_and_b32_e32 v236, 0x30, v236
	v_xor_b32_e32 v236, v236, v108
	ds_write_b128 v236, v[72:75]
	v_add_f32_e32 v72, v64, v68
	v_add_f32_e32 v69, v65, v69
	v_min_f32_e32 v68, 0, v72
	v_mul_f32_e64 v72, |v72|, s43
	v_mul_f32_e64 v73, |v69|, s43
	v_add_f32_e32 v74, v66, v70
	v_add_f32_e32 v71, v67, v71
	v_exp_f32_e32 v72, v72
	v_exp_f32_e32 v73, v73
	v_min_f32_e32 v70, 0, v74
	v_mul_f32_e64 v74, |v74|, s43
	v_mul_f32_e64 v75, |v71|, s43
	v_exp_f32_e32 v74, v74
	v_exp_f32_e32 v75, v75
	v_add_f32_e32 v72, 1.0, v72
	v_add_f32_e32 v73, 1.0, v73
	v_log_f32_e32 v72, v72
	v_log_f32_e32 v73, v73
	v_add_f32_e32 v74, 1.0, v74
	v_add_f32_e32 v75, 1.0, v75
	v_log_f32_e32 v74, v74
	v_log_f32_e32 v75, v75
	v_mfma_f32_16x16x32_bf16 v[52:55], v[56:59], v[52:55], 0
	v_min_f32_e32 v69, 0, v69
	v_xor_b32_e32 v73, 0x80000000, v73
	v_xor_b32_e32 v72, 0x80000000, v72
	v_mfma_f32_16x16x32_bf16 v[60:63], v[56:59], v[60:63], 0
	v_min_f32_e32 v71, 0, v71
	v_pk_fma_f32 v[68:69], v[72:73], s[46:47], v[68:69] op_sel_hi:[1,0,1]
	v_xor_b32_e32 v73, 0x80000000, v75
	v_xor_b32_e32 v72, 0x80000000, v74
	v_pk_fma_f32 v[70:71], v[72:73], s[46:47], v[70:71] op_sel_hi:[1,0,1]
	v_pk_mul_f32 v[68:69], v[68:69], s[50:51] op_sel_hi:[1,0]
	v_pk_mul_f32 v[70:71], v[70:71], s[50:51] op_sel_hi:[1,0]
	v_add_f32_e32 v56, v64, v52
	v_add_f32_e32 v53, v65, v53
	v_lshlrev_b32_e32 v237, 3, v204
	v_and_b32_e32 v237, 0x30, v237
	v_xor_b32_e32 v237, v237, v108
	ds_write_b128 v237, v[68:71] offset:8192
	v_add_f32_e32 v68, v64, v60
	v_add_f32_e32 v61, v65, v61
	v_min_f32_e32 v52, 0, v56
	v_mul_f32_e64 v56, |v56|, s43
	v_mul_f32_e64 v57, |v53|, s43
	v_add_f32_e32 v58, v66, v54
	v_add_f32_e32 v55, v67, v55
	v_min_f32_e32 v60, 0, v68
	v_mul_f32_e64 v68, |v68|, s43
	v_mul_f32_e64 v69, |v61|, s43
	v_add_f32_e32 v70, v66, v62
	v_add_f32_e32 v63, v67, v63
	v_exp_f32_e32 v56, v56
	v_exp_f32_e32 v57, v57
	v_min_f32_e32 v54, 0, v58
	v_mul_f32_e64 v58, |v58|, s43
	v_mul_f32_e64 v59, |v55|, s43
	v_exp_f32_e32 v68, v68
	v_exp_f32_e32 v69, v69
	v_min_f32_e32 v62, 0, v70
	v_mul_f32_e64 v70, |v70|, s43
	v_mul_f32_e64 v71, |v63|, s43
	v_exp_f32_e32 v58, v58
	v_exp_f32_e32 v59, v59
	v_exp_f32_e32 v70, v70
	v_exp_f32_e32 v71, v71
	v_add_f32_e32 v56, 1.0, v56
	v_add_f32_e32 v57, 1.0, v57
	v_add_f32_e32 v68, 1.0, v68
	v_add_f32_e32 v69, 1.0, v69
	v_log_f32_e32 v56, v56
	v_log_f32_e32 v57, v57
	v_add_f32_e32 v58, 1.0, v58
	v_add_f32_e32 v59, 1.0, v59
	v_log_f32_e32 v68, v68
	v_log_f32_e32 v69, v69
	v_add_f32_e32 v70, 1.0, v70
	v_add_f32_e32 v71, 1.0, v71
	v_log_f32_e32 v58, v58
	v_log_f32_e32 v59, v59
	v_log_f32_e32 v70, v70
	v_log_f32_e32 v71, v71
	v_min_f32_e32 v53, 0, v53
	v_xor_b32_e32 v57, 0x80000000, v57
	v_xor_b32_e32 v56, 0x80000000, v56
	v_min_f32_e32 v61, 0, v61
	v_xor_b32_e32 v69, 0x80000000, v69
	v_xor_b32_e32 v68, 0x80000000, v68
	v_min_f32_e32 v55, 0, v55
	v_pk_fma_f32 v[52:53], v[56:57], s[46:47], v[52:53] op_sel_hi:[1,0,1]
	v_xor_b32_e32 v57, 0x80000000, v59
	v_xor_b32_e32 v56, 0x80000000, v58
	v_min_f32_e32 v63, 0, v63
	v_pk_fma_f32 v[60:61], v[68:69], s[46:47], v[60:61] op_sel_hi:[1,0,1]
	v_xor_b32_e32 v69, 0x80000000, v71
	v_xor_b32_e32 v68, 0x80000000, v70
	v_pk_fma_f32 v[54:55], v[56:57], s[46:47], v[54:55] op_sel_hi:[1,0,1]
	v_or_b32_e32 v121, 0xa00, v105
	v_or_b32_e32 v122, 0xc00, v105
	v_or_b32_e32 v123, 0xe00, v105
	v_pk_fma_f32 v[62:63], v[68:69], s[46:47], v[62:63] op_sel_hi:[1,0,1]
	v_pk_mul_f32 v[54:55], v[54:55], s[50:51] op_sel_hi:[1,0]
	v_pk_mul_f32 v[52:53], v[52:53], s[50:51] op_sel_hi:[1,0]
	v_or_b32_e32 v124, 0x1000, v105
	v_or_b32_e32 v131, 0x1e00, v105
	v_pk_mul_f32 v[62:63], v[62:63], s[50:51] op_sel_hi:[1,0]
	v_pk_mul_f32 v[60:61], v[60:61], s[50:51] op_sel_hi:[1,0]
	v_lshlrev_b32_e32 v236, 3, v204
	v_and_b32_e32 v236, 0x30, v236
	v_xor_b32_e32 v236, v236, v108
	ds_write_b128 v236, v[52:55] offset:24576
	v_sub_u32_e32 v52, v104, v105
	v_sub_u32_e32 v53, v104, v93
	v_sub_u32_e32 v54, v104, v118
	v_sub_u32_e32 v55, v104, v119
	v_sub_u32_e32 v56, v104, v120
	v_sub_u32_e32 v57, v104, v121
	v_sub_u32_e32 v58, v104, v122
	v_sub_u32_e32 v59, v104, v123
	v_or_b32_e32 v125, 0x1200, v105
	v_or_b32_e32 v126, 0x1400, v105
	v_or_b32_e32 v127, 0x1600, v105
	v_or_b32_e32 v128, 0x1800, v105
	v_or_b32_e32 v129, 0x1a00, v105
	v_or_b32_e32 v130, 0x1c00, v105
	v_lshlrev_b32_e32 v237, 3, v204
	v_and_b32_e32 v237, 0x30, v237
	v_xor_b32_e32 v237, v237, v108
	ds_write_b128 v237, v[60:63] offset:16384
	s_waitcnt lgkmcnt(0)
	s_barrier
	v_xor_b32_e32 v236, 48, v52
	ds_read_b32 v52, v236 offset:32256
	v_xor_b32_e32 v237, 48, v53
	ds_read_b32 v53, v237 offset:32256
	v_xor_b32_e32 v236, 32, v54
	ds_read_b32 v54, v236 offset:32256
	v_xor_b32_e32 v237, 32, v55
	ds_read_b32 v55, v237 offset:32256
	v_xor_b32_e32 v236, 16, v56
	ds_read_b32 v56, v236 offset:32256
	v_xor_b32_e32 v237, 16, v57
	ds_read_b32 v57, v237 offset:32256
	ds_read_b32 v58, v58 offset:32256
	ds_read_b32 v59, v59 offset:32256
	v_sub_u32_e32 v60, v104, v124
	v_sub_u32_e32 v67, v104, v131
	s_waitcnt lgkmcnt(7)
	v_add_f32_e32 v68, 0, v52
	v_sub_u32_e32 v61, v104, v125
	v_sub_u32_e32 v62, v104, v126
	v_sub_u32_e32 v63, v104, v127
	v_sub_u32_e32 v64, v104, v128
	v_sub_u32_e32 v65, v104, v129
	v_sub_u32_e32 v66, v104, v130
	v_xor_b32_e32 v236, 48, v60
	ds_read_b32 v60, v236 offset:32256
	v_xor_b32_e32 v237, 48, v61
	ds_read_b32 v69, v237 offset:32256
	v_xor_b32_e32 v236, 32, v62
	ds_read_b32 v70, v236 offset:32256
	v_xor_b32_e32 v237, 32, v63
	ds_read_b32 v71, v237 offset:32256
	v_xor_b32_e32 v236, 16, v64
	ds_read_b32 v72, v236 offset:32256
	v_xor_b32_e32 v237, 16, v65
	ds_read_b32 v73, v237 offset:32256
	ds_read_b32 v74, v66 offset:32256
	ds_read_b32 v75, v67 offset:32256
	s_waitcnt lgkmcnt(14)
	v_add_f32_e32 v67, v68, v53
	s_waitcnt lgkmcnt(13)
	v_add_f32_e32 v66, v67, v54
	s_waitcnt lgkmcnt(12)
	v_add_f32_e32 v65, v66, v55
	s_waitcnt lgkmcnt(11)
	v_add_f32_e32 v64, v65, v56
	s_waitcnt lgkmcnt(10)
	v_add_f32_e32 v63, v64, v57
	s_waitcnt lgkmcnt(9)
	v_add_f32_e32 v62, v63, v58
	s_waitcnt lgkmcnt(8)
	v_add_f32_e32 v61, v62, v59
	s_waitcnt lgkmcnt(7)
	v_add_f32_e32 v60, v61, v60
	s_waitcnt lgkmcnt(6)
	v_add_f32_e32 v59, v60, v69
	s_waitcnt lgkmcnt(5)
	v_add_f32_e32 v58, v59, v70
	s_waitcnt lgkmcnt(4)
	v_add_f32_e32 v57, v58, v71
	s_waitcnt lgkmcnt(3)
	v_add_f32_e32 v55, v57, v72
	s_waitcnt lgkmcnt(2)
	v_add_f32_e32 v54, v55, v73
	s_waitcnt lgkmcnt(1)
	v_add_f32_e32 v53, v54, v74
	s_waitcnt lgkmcnt(0)
	v_add_f32_e32 v52, v53, v75
	v_mov_b32_e32 v56, 0
	ds_write_b32 v107, v52
	s_waitcnt lgkmcnt(0)
	s_barrier
	s_and_saveexec_b64 s[52:53], s[10:11]
	s_cbranch_execnz .LBB0_1372
	s_or_b64 exec, exec, s[52:53]
	s_and_saveexec_b64 s[10:11], s[14:15]
	s_cbranch_execnz .LBB0_1373

.LBB0_1364:
	s_or_b64 exec, exec, s[10:11]
	v_sub_u32_e32 v69, 0, v105
	v_sub_u32_e32 v70, 0, v93
	v_add_f32_e32 v68, v68, v56
	v_add_u32_e32 v69, v104, v69
	v_sub_u32_e32 v71, 0, v118
	v_xor_b32_e32 v236, 48, v69
	ds_write_b32 v236, v68 offset:32256
	v_add_f32_e32 v67, v67, v56
	v_add_u32_e32 v68, v104, v70
	v_sub_u32_e32 v72, 0, v119
	v_xor_b32_e32 v237, 48, v68
	ds_write_b32 v237, v67 offset:32256
	v_add_f32_e32 v66, v66, v56
	v_add_u32_e32 v67, v104, v71
	v_sub_u32_e32 v73, 0, v120
	v_xor_b32_e32 v236, 32, v67
	ds_write_b32 v236, v66 offset:32256
	v_add_f32_e32 v65, v65, v56
	v_add_u32_e32 v66, v104, v72
	v_sub_u32_e32 v74, 0, v121
	v_xor_b32_e32 v237, 32, v66
	ds_write_b32 v237, v65 offset:32256
	v_add_f32_e32 v64, v64, v56
	v_add_u32_e32 v65, v104, v73
	v_sub_u32_e32 v75, 0, v122
	v_xor_b32_e32 v236, 16, v65
	ds_write_b32 v236, v64 offset:32256
	v_add_f32_e32 v63, v63, v56
	v_add_u32_e32 v64, v104, v74
	v_sub_u32_e32 v93, 0, v123
	v_xor_b32_e32 v237, 16, v64
	ds_write_b32 v237, v63 offset:32256
	v_add_f32_e32 v62, v62, v56
	v_add_u32_e32 v63, v104, v75
	v_sub_u32_e32 v105, 0, v124
	ds_write_b32 v63, v62 offset:32256
	v_add_f32_e32 v61, v61, v56
	v_add_u32_e32 v62, v104, v93
	v_sub_u32_e32 v106, 0, v125
	ds_write_b32 v62, v61 offset:32256
	v_add_f32_e32 v60, v60, v56
	v_add_u32_e32 v61, v104, v105
	v_sub_u32_e32 v107, 0, v126
	v_xor_b32_e32 v236, 48, v61
	ds_write_b32 v236, v60 offset:32256
	v_add_f32_e32 v59, v59, v56
	v_add_u32_e32 v60, v104, v106
	v_sub_u32_e32 v108, 0, v127
	v_xor_b32_e32 v237, 48, v60
	ds_write_b32 v237, v59 offset:32256
	v_add_f32_e32 v58, v58, v56
	v_add_u32_e32 v59, v104, v107
	v_sub_u32_e32 v118, 0, v128
	v_xor_b32_e32 v236, 32, v59
	ds_write_b32 v236, v58 offset:32256
	v_add_f32_e32 v57, v57, v56
	v_add_u32_e32 v58, v104, v108
	v_sub_u32_e32 v119, 0, v129
	v_xor_b32_e32 v237, 32, v58
	ds_write_b32 v237, v57 offset:32256
	v_add_f32_e32 v55, v55, v56
	v_add_u32_e32 v57, v104, v118
	v_sub_u32_e32 v120, 0, v130
	v_xor_b32_e32 v236, 16, v57
	ds_write_b32 v236, v55 offset:32256
	v_add_f32_e32 v54, v54, v56
	v_add_u32_e32 v55, v104, v119
	v_sub_u32_e32 v121, 0, v131
	v_xor_b32_e32 v237, 16, v55
	ds_write_b32 v237, v54 offset:32256
	v_add_f32_e32 v53, v53, v56
	v_add_u32_e32 v54, v104, v120
	ds_write_b32 v54, v53 offset:32256
	v_add_f32_e32 v52, v52, v56
	v_add_u32_e32 v53, v104, v121
	ds_write_b32 v53, v52 offset:32256
	s_waitcnt lgkmcnt(0)
	s_barrier
	v_lshrrev_b32_e32 v236, 1, v204
	v_and_b32_e32 v236, 0x30, v236
	v_xor_b32_e32 v236, v236, v114
	ds_read_b128 v[52:55], v236
	ds_read_b128 v[56:59], v110
	v_xor_b32_e32 v237, 16, v110
	ds_read_b128 v[60:63], v237
	v_lshrrev_b32_e32 v236, 1, v204
	v_and_b32_e32 v236, 0x30, v236
	v_xor_b32_e32 v236, 16, v236
	v_xor_b32_e32 v236, v236, v114
	ds_read_b128 v[64:67], v236
	s_waitcnt lgkmcnt(2)
	v_sub_f32_e32 v52, v56, v52
	v_sub_f32_e32 v53, v57, v53
	v_sub_f32_e32 v54, v58, v54
	v_sub_f32_e32 v55, v59, v55
	s_waitcnt lgkmcnt(0)
	v_sub_f32_e32 v64, v60, v64
	v_sub_f32_e32 v65, v61, v65
	v_sub_f32_e32 v66, v62, v66
	v_sub_f32_e32 v67, v63, v67
	v_mul_f32_e32 v52, 0x3fb8aa3b, v52
	v_mul_f32_e32 v53, 0x3fb8aa3b, v53
	v_mul_f32_e32 v54, 0x3fb8aa3b, v54
	v_mul_f32_e32 v55, 0x3fb8aa3b, v55
	v_mul_f32_e32 v64, 0x3fb8aa3b, v64
	v_mul_f32_e32 v65, 0x3fb8aa3b, v65
	v_mul_f32_e32 v66, 0x3fb8aa3b, v66
	v_mul_f32_e32 v67, 0x3fb8aa3b, v67
	v_exp_f32_e32 v52, v52
	v_exp_f32_e32 v53, v53
	v_exp_f32_e32 v54, v54
	v_exp_f32_e32 v55, v55
	v_exp_f32_e32 v64, v64
	v_exp_f32_e32 v65, v65
	v_exp_f32_e32 v66, v66
	v_exp_f32_e32 v67, v67
	v_pk_mul_f32 v[52:53], v[52:53], v[82:83]
	v_pk_mul_f32 v[54:55], v[54:55], v[84:85]
	v_pk_mul_f32 v[64:65], v[64:65], v[86:87]
	v_pk_mul_f32 v[66:67], v[66:67], v[88:89]
	v_cvt_pk_bf16_f32 v52, v52, v53
	v_cvt_pk_bf16_f32 v53, v54, v55
	v_cvt_pk_bf16_f32 v54, v64, v65
	v_cvt_pk_bf16_f32 v55, v66, v67
	ds_write_b128 v109, v[52:55] offset:32768
	v_lshrrev_b32_e32 v237, 1, v204
	v_and_b32_e32 v237, 0x30, v237
	v_xor_b32_e32 v237, v237, v115
	ds_read_b128 v[52:55], v237
	v_lshrrev_b32_e32 v236, 1, v204
	v_and_b32_e32 v236, 0x30, v236
	v_xor_b32_e32 v236, 16, v236
	v_xor_b32_e32 v236, v236, v115
	ds_read_b128 v[64:67], v236
	s_waitcnt lgkmcnt(1)
	v_sub_f32_e32 v52, v56, v52
	v_sub_f32_e32 v53, v57, v53
	v_sub_f32_e32 v54, v58, v54
	v_sub_f32_e32 v55, v59, v55
	s_waitcnt lgkmcnt(0)
	v_sub_f32_e32 v56, v60, v64
	v_sub_f32_e32 v57, v61, v65
	v_sub_f32_e32 v58, v62, v66
	v_sub_f32_e32 v59, v63, v67
	v_mul_f32_e32 v52, 0x3fb8aa3b, v52
	v_mul_f32_e32 v53, 0x3fb8aa3b, v53
	v_mul_f32_e32 v54, 0x3fb8aa3b, v54
	v_mul_f32_e32 v55, 0x3fb8aa3b, v55
	v_mul_f32_e32 v56, 0x3fb8aa3b, v56
	v_mul_f32_e32 v57, 0x3fb8aa3b, v57
	v_mul_f32_e32 v58, 0x3fb8aa3b, v58
	v_mul_f32_e32 v59, 0x3fb8aa3b, v59
	v_exp_f32_e32 v52, v52
	v_exp_f32_e32 v53, v53
	v_exp_f32_e32 v54, v54
	v_exp_f32_e32 v55, v55
	v_exp_f32_e32 v56, v56
	v_exp_f32_e32 v57, v57
	v_exp_f32_e32 v58, v58
	v_exp_f32_e32 v59, v59
	v_pk_mul_f32 v[52:53], v[52:53], v[76:77]
	v_pk_mul_f32 v[54:55], v[54:55], v[78:79]
	v_pk_mul_f32 v[56:57], v[56:57], v[80:81]
	v_pk_mul_f32 v[58:59], v[58:59], v[90:91]
	v_cvt_pk_bf16_f32 v52, v52, v53
	v_cvt_pk_bf16_f32 v53, v54, v55
	v_cvt_pk_bf16_f32 v54, v56, v57
	v_cvt_pk_bf16_f32 v55, v58, v59
	ds_write_b128 v109, v[52:55] offset:41984
	s_and_saveexec_b64 s[10:11], s[12:13]
	s_cbranch_execz .LBB0_1295
	v_lshrrev_b32_e32 v237, 4, v204
	v_and_b32_e32 v237, 0x30, v237
	v_xor_b32_e32 v237, v237, v112
	ds_read_b32 v52, v237
	s_ashr_i32 s59, s58, 31
	s_lshl_b64 s[12:13], s[58:59], 15
	s_add_u32 s12, s0, s12
	s_addc_u32 s13, s1, s13
	s_waitcnt lgkmcnt(0)
	v_mul_f32_e32 v52, 0x3fb8aa3b, v52
	v_exp_f32_e32 v52, v52
	s_add_u32 s12, s12, s2
	s_addc_u32 s13, s13, 0
	v_lshl_add_u64 v[10:11], v[10:11], 2, s[12:13]
	global_store_dword v[10:11], v52, off
	s_branch .LBB0_1295

.LBB0_1449:
	v_lshlrev_b32_e32 v86, 2, v2
	v_and_b32_e32 v87, 0x1fc, v86
	v_add_u32_e32 v104, 0, v87
	v_add_u32_e32 v107, s92, v86
	v_add_u32_e32 v106, s92, v87
	s_nop 0
	v_mfma_f32_16x16x32_bf16 v[86:89], v[76:79], v[72:75], 0
	v_lshlrev_b32_e32 v84, 9, v92
	v_and_b32_e32 v85, 0xffffffc0, v2
	v_add3_u32 v85, 0, v84, v85
	v_add_u32_e32 v108, v85, v0
	v_ashrrev_i32_e32 v84, 7, v2
	s_nop 0
	s_nop 1
	v_add_f32_e32 v90, v80, v86
	v_add_f32_e32 v87, v81, v87
	v_min_f32_e32 v86, 0, v90
	v_mul_f32_e64 v90, |v90|, s49
	v_mul_f32_e64 v91, |v87|, s49
	v_add_f32_e32 v95, v82, v88
	v_add_f32_e32 v89, v83, v89
	v_exp_f32_e32 v90, v90
	v_exp_f32_e32 v91, v91
	v_min_f32_e32 v88, 0, v95
	v_mul_f32_e64 v95, |v95|, s49
	v_mul_f32_e64 v96, |v89|, s49
	v_exp_f32_e32 v95, v95
	v_exp_f32_e32 v96, v96
	v_add_f32_e32 v90, 1.0, v90
	v_add_f32_e32 v91, 1.0, v91
	v_log_f32_e32 v90, v90
	v_log_f32_e32 v91, v91
	v_add_f32_e32 v95, 1.0, v95
	v_add_f32_e32 v96, 1.0, v96
	v_log_f32_e32 v95, v95
	v_log_f32_e32 v96, v96
	v_min_f32_e32 v87, 0, v87
	v_xor_b32_e32 v91, 0x80000000, v91
	v_xor_b32_e32 v90, 0x80000000, v90
	v_min_f32_e32 v89, 0, v89
	v_pk_fma_f32 v[86:87], v[90:91], s[52:53], v[86:87] op_sel_hi:[1,0,1]
	v_xor_b32_e32 v91, 0x80000000, v96
	v_xor_b32_e32 v90, 0x80000000, v95
	v_pk_fma_f32 v[88:89], v[90:91], s[52:53], v[88:89] op_sel_hi:[1,0,1]
	v_pk_mul_f32 v[86:87], v[86:87], s[54:55] op_sel_hi:[1,0]
	v_pk_mul_f32 v[88:89], v[88:89], s[54:55] op_sel_hi:[1,0]
	v_lshlrev_b32_e32 v236, 3, v204
	v_and_b32_e32 v236, 0x30, v236
	v_xor_b32_e32 v236, v236, v108
	ds_write_b128 v236, v[86:89]
	v_mfma_f32_16x16x32_bf16 v[86:89], v[76:79], v[68:71], 0
	v_lshlrev_b32_e32 v105, 13, v84
	v_cmp_lt_i32_e64 s[10:11], 0, v84
	v_mov_b32_e32 v117, 0
	s_nop 4
	v_add_f32_e32 v85, v81, v87
	v_mul_f32_e64 v87, |v85|, s49
	v_exp_f32_e32 v90, v87
	v_add_f32_e32 v0, v80, v86
	v_min_f32_e32 v87, 0, v85
	v_min_f32_e32 v86, 0, v0
	v_add_f32_e32 v85, 1.0, v90
	v_add_f32_e32 v90, v82, v88
	v_mul_f32_e64 v0, |v0|, s49
	v_min_f32_e32 v88, 0, v90
	v_mul_f32_e64 v90, |v90|, s49
	v_add_f32_e32 v89, v83, v89
	v_exp_f32_e32 v0, v0
	v_exp_f32_e32 v90, v90
	v_mul_f32_e64 v91, |v89|, s49
	v_exp_f32_e32 v91, v91
	v_add_f32_e32 v0, 1.0, v0
	v_add_f32_e32 v90, 1.0, v90
	v_log_f32_e32 v0, v0
	v_log_f32_e32 v85, v85
	v_log_f32_e32 v95, v90
	v_add_f32_e32 v90, 1.0, v91
	v_log_f32_e32 v96, v90
	v_xor_b32_e32 v91, 0x80000000, v85
	v_xor_b32_e32 v90, 0x80000000, v0
	v_min_f32_e32 v89, 0, v89
	v_pk_fma_f32 v[86:87], v[90:91], s[52:53], v[86:87] op_sel_hi:[1,0,1]
	v_xor_b32_e32 v91, 0x80000000, v96
	v_xor_b32_e32 v90, 0x80000000, v95
	v_pk_fma_f32 v[88:89], v[90:91], s[52:53], v[88:89] op_sel_hi:[1,0,1]
	v_pk_mul_f32 v[86:87], v[86:87], s[54:55] op_sel_hi:[1,0]
	v_pk_mul_f32 v[88:89], v[88:89], s[54:55] op_sel_hi:[1,0]
	v_lshlrev_b32_e32 v237, 3, v204
	v_and_b32_e32 v237, 0x30, v237
	v_xor_b32_e32 v237, v237, v108
	ds_write_b128 v237, v[86:89] offset:8192
	v_mfma_f32_16x16x32_bf16 v[86:89], v[76:79], v[60:63], 0
	v_mfma_f32_16x16x32_bf16 v[76:79], v[76:79], v[52:55], 0
	s_nop 6
	v_add_f32_e32 v85, v81, v87
	v_mul_f32_e64 v87, |v85|, s49
	v_exp_f32_e32 v90, v87
	v_add_f32_e32 v0, v80, v86
	v_min_f32_e32 v86, 0, v0
	v_mul_f32_e64 v0, |v0|, s49
	v_exp_f32_e32 v0, v0
	v_min_f32_e32 v87, 0, v85
	v_add_f32_e32 v85, 1.0, v90
	v_add_f32_e32 v90, v82, v88
	v_min_f32_e32 v88, 0, v90
	v_mul_f32_e64 v90, |v90|, s49
	v_add_f32_e32 v89, v83, v89
	v_exp_f32_e32 v90, v90
	v_mul_f32_e64 v91, |v89|, s49
	v_add_f32_e32 v0, 1.0, v0
	v_exp_f32_e32 v91, v91
	v_log_f32_e32 v0, v0
	v_add_f32_e32 v90, 1.0, v90
	v_log_f32_e32 v95, v90
	v_add_f32_e32 v90, 1.0, v91
	v_log_f32_e32 v96, v90
	v_xor_b32_e32 v90, 0x80000000, v0
	v_add_f32_e32 v0, v80, v76
	v_add_f32_e32 v77, v81, v77
	v_add_f32_e32 v81, v82, v78
	v_min_f32_e32 v76, 0, v0
	v_mul_f32_e64 v0, |v0|, s49
	v_mul_f32_e64 v80, |v77|, s49
	v_min_f32_e32 v78, 0, v81
	v_mul_f32_e64 v81, |v81|, s49
	v_add_f32_e32 v79, v83, v79
	v_exp_f32_e32 v0, v0
	v_exp_f32_e32 v80, v80
	v_exp_f32_e32 v81, v81
	v_mul_f32_e64 v82, |v79|, s49
	v_exp_f32_e32 v82, v82
	v_add_f32_e32 v0, 1.0, v0
	v_add_f32_e32 v80, 1.0, v80
	v_add_f32_e32 v81, 1.0, v81
	v_log_f32_e32 v85, v85
	v_log_f32_e32 v0, v0
	v_log_f32_e32 v80, v80
	v_log_f32_e32 v83, v81
	v_add_f32_e32 v81, 1.0, v82
	v_log_f32_e32 v82, v81
	v_xor_b32_e32 v91, 0x80000000, v85
	v_min_f32_e32 v77, 0, v77
	v_xor_b32_e32 v81, 0x80000000, v80
	v_xor_b32_e32 v80, 0x80000000, v0
	v_min_f32_e32 v89, 0, v89
	v_pk_fma_f32 v[86:87], v[90:91], s[52:53], v[86:87] op_sel_hi:[1,0,1]
	v_xor_b32_e32 v91, 0x80000000, v96
	v_xor_b32_e32 v90, 0x80000000, v95
	v_min_f32_e32 v79, 0, v79
	v_pk_fma_f32 v[76:77], v[80:81], s[52:53], v[76:77] op_sel_hi:[1,0,1]
	v_xor_b32_e32 v81, 0x80000000, v82
	v_xor_b32_e32 v80, 0x80000000, v83
	v_pk_fma_f32 v[88:89], v[90:91], s[52:53], v[88:89] op_sel_hi:[1,0,1]
	v_pk_fma_f32 v[78:79], v[80:81], s[52:53], v[78:79] op_sel_hi:[1,0,1]
	v_pk_mul_f32 v[88:89], v[88:89], s[54:55] op_sel_hi:[1,0]
	v_pk_mul_f32 v[86:87], v[86:87], s[54:55] op_sel_hi:[1,0]
	v_pk_mul_f32 v[78:79], v[78:79], s[54:55] op_sel_hi:[1,0]
	v_pk_mul_f32 v[76:77], v[76:77], s[54:55] op_sel_hi:[1,0]
	v_add_u32_e32 v0, v104, v105
	v_lshlrev_b32_e32 v236, 3, v204
	v_and_b32_e32 v236, 0x30, v236
	v_xor_b32_e32 v236, v236, v108
	ds_write_b128 v236, v[86:89] offset:16384
	v_lshlrev_b32_e32 v237, 3, v204
	v_and_b32_e32 v237, 0x30, v237
	v_xor_b32_e32 v237, v237, v108
	ds_write_b128 v237, v[76:79] offset:24576
	s_waitcnt lgkmcnt(0)
	s_barrier
	ds_read2st64_b32 v[76:77], v0 offset1:2
	v_xor_b32_e32 v236, 16, v0
	ds_read2st64_b32 v[78:79], v236 offset0:4 offset1:6
	v_xor_b32_e32 v237, 32, v0
	ds_read2st64_b32 v[80:81], v237 offset0:8 offset1:10
	v_xor_b32_e32 v236, 48, v0
	ds_read2st64_b32 v[82:83], v236 offset0:12 offset1:14
	ds_read2st64_b32 v[86:87], v0 offset0:16 offset1:18
	v_xor_b32_e32 v237, 16, v0
	ds_read2st64_b32 v[88:89], v237 offset0:20 offset1:22
	v_xor_b32_e32 v236, 32, v0
	ds_read2st64_b32 v[90:91], v236 offset0:24 offset1:26
	v_xor_b32_e32 v237, 48, v0
	ds_read2st64_b32 v[118:119], v237 offset0:28 offset1:30
	s_waitcnt lgkmcnt(7)
	v_add_f32_e32 v115, 0, v76
	v_add_f32_e32 v116, v115, v77
	s_waitcnt lgkmcnt(6)
	v_add_f32_e32 v113, v116, v78
	v_add_f32_e32 v114, v113, v79
	s_waitcnt lgkmcnt(5)
	v_add_f32_e32 v111, v114, v80
	v_add_f32_e32 v112, v111, v81
	s_waitcnt lgkmcnt(4)
	v_add_f32_e32 v101, v112, v82
	v_add_f32_e32 v109, v101, v83
	s_waitcnt lgkmcnt(3)
	v_add_f32_e32 v99, v109, v86
	v_add_f32_e32 v100, v99, v87
	s_waitcnt lgkmcnt(2)
	v_add_f32_e32 v97, v100, v88
	v_add_f32_e32 v98, v97, v89
	s_waitcnt lgkmcnt(1)
	v_add_f32_e32 v95, v98, v90
	v_add_f32_e32 v96, v95, v91
	s_waitcnt lgkmcnt(0)
	v_add_f32_e32 v90, v96, v118
	v_add_f32_e32 v91, v90, v119
	ds_write_b32 v107, v91
	s_waitcnt lgkmcnt(0)
	s_barrier
	s_and_saveexec_b64 s[12:13], s[10:11]
	s_cbranch_execnz .LBB0_1504
	s_or_b64 exec, exec, s[12:13]
	v_cmp_lt_i32_e64 s[14:15], 1, v84
	s_and_saveexec_b64 s[12:13], s[14:15]
	s_cbranch_execnz .LBB0_1505

.LBB0_1453:
	s_or_b64 exec, exec, s[12:13]
	v_lshlrev_b32_e32 v110, 3, v2
	v_and_b32_e32 v120, 0x78, v110
	v_ashrrev_i32_e32 v128, 4, v2
	v_add_f32_e32 v115, v115, v117
	v_add_f32_e32 v116, v116, v117
	v_add_f32_e32 v113, v113, v117
	v_add_f32_e32 v114, v114, v117
	v_add_f32_e32 v111, v111, v117
	v_add_f32_e32 v112, v112, v117
	v_add_f32_e32 v101, v101, v117
	v_add_f32_e32 v109, v109, v117
	v_add_f32_e32 v99, v99, v117
	v_add_f32_e32 v100, v100, v117
	v_add_f32_e32 v97, v97, v117
	v_add_f32_e32 v98, v98, v117
	v_add_f32_e32 v95, v95, v117
	v_add_f32_e32 v96, v96, v117
	v_add_f32_e32 v90, v90, v117
	v_add_f32_e32 v91, v91, v117
	v_lshl_add_u32 v110, v120, 2, 0
	ds_write2st64_b32 v0, v115, v116 offset1:2
	v_xor_b32_e32 v236, 16, v0
	ds_write2st64_b32 v236, v113, v114 offset0:4 offset1:6
	v_xor_b32_e32 v237, 32, v0
	ds_write2st64_b32 v237, v111, v112 offset0:8 offset1:10
	v_xor_b32_e32 v236, 48, v0
	ds_write2st64_b32 v236, v101, v109 offset0:12 offset1:14
	ds_write2st64_b32 v0, v99, v100 offset0:16 offset1:18
	v_xor_b32_e32 v237, 16, v0
	ds_write2st64_b32 v237, v97, v98 offset0:20 offset1:22
	v_xor_b32_e32 v236, 32, v0
	ds_write2st64_b32 v236, v95, v96 offset0:24 offset1:26
	v_xor_b32_e32 v237, 48, v0
	ds_write2st64_b32 v237, v90, v91 offset0:28 offset1:30
	v_lshlrev_b32_e32 v0, 9, v128
	v_add_u32_e32 v114, v110, v0
	s_waitcnt lgkmcnt(0)
	s_barrier
	v_xor_b32_e32 v236, 48, v110
	ds_read_b128 v[96:99], v236 offset:32256
	v_lshrrev_b32_e32 v237, 1, v204
	v_and_b32_e32 v237, 0x30, v237
	v_xor_b32_e32 v237, v237, v114
	ds_read_b128 v[116:119], v237
	v_lshlrev_b32_e32 v90, 1, v120
	v_xor_b32_e32 v236, 32, v110
	ds_read_b128 v[120:123], v236 offset:32256
	v_lshrrev_b32_e32 v237, 1, v204
	v_and_b32_e32 v237, 0x30, v237
	v_xor_b32_e32 v237, 16, v237
	v_xor_b32_e32 v237, v237, v114
	ds_read_b128 v[124:127], v237
	v_sub_u32_e32 v95, v110, v90
	v_lshlrev_b32_e32 v82, 16, v28
	s_waitcnt lgkmcnt(2)
	v_sub_f32_e32 v90, v96, v116
	v_sub_f32_e32 v91, v97, v117
	s_waitcnt lgkmcnt(0)
	v_sub_f32_e32 v109, v120, v124
	v_mul_f32_e32 v109, 0x3fb8aa3b, v109
	v_exp_f32_e32 v112, v109
	v_sub_f32_e32 v109, v121, v125
	v_mul_f32_e32 v109, 0x3fb8aa3b, v109
	v_exp_f32_e32 v113, v109
	v_sub_f32_e32 v109, v122, v126
	v_mul_f32_e32 v109, 0x3fb8aa3b, v109
	v_mul_f32_e32 v90, 0x3fb8aa3b, v90
	v_mul_f32_e32 v91, 0x3fb8aa3b, v91
	v_sub_f32_e32 v100, v98, v118
	v_sub_f32_e32 v101, v99, v119
	v_exp_f32_e32 v116, v109
	v_sub_f32_e32 v109, v123, v127
	v_exp_f32_e32 v90, v90
	v_exp_f32_e32 v91, v91
	v_mul_f32_e32 v100, 0x3fb8aa3b, v100
	v_mul_f32_e32 v101, 0x3fb8aa3b, v101
	v_mul_f32_e32 v109, 0x3fb8aa3b, v109
	v_exp_f32_e32 v100, v100
	v_exp_f32_e32 v101, v101
	v_exp_f32_e32 v117, v109
	v_and_b32_e32 v83, 0xffff0000, v28
	v_lshlrev_b32_e32 v84, 16, v29
	v_and_b32_e32 v85, 0xffff0000, v29
	v_lshlrev_b32_e32 v86, 16, v30
	v_and_b32_e32 v87, 0xffff0000, v30
	v_lshlrev_b32_e32 v88, 16, v31
	v_and_b32_e32 v89, 0xffff0000, v31
	v_pk_mul_f32 v[90:91], v[90:91], v[82:83]
	v_pk_mul_f32 v[100:101], v[100:101], v[84:85]
	v_pk_mul_f32 v[112:113], v[112:113], v[86:87]
	v_pk_mul_f32 v[124:125], v[116:117], v[88:89]
	v_cvt_pk_bf16_f32 v116, v90, v91
	v_mul_lo_u32 v90, v128, s55
	v_cvt_pk_bf16_f32 v117, v100, v101
	v_cvt_pk_bf16_f32 v118, v112, v113
	v_cvt_pk_bf16_f32 v119, v124, v125
	v_add_u32_e32 v109, v95, v90
	v_add_u32_e32 v0, 0x4000, v0
	ds_write_b128 v109, v[116:119] offset:32768
	v_add_u32_e32 v115, v110, v0
	v_lshrrev_b32_e32 v236, 1, v204
	v_and_b32_e32 v236, 0x30, v236
	v_xor_b32_e32 v236, v236, v115
	ds_read_b128 v[116:119], v236
	v_lshrrev_b32_e32 v237, 1, v204
	v_and_b32_e32 v237, 0x30, v237
	v_xor_b32_e32 v237, 16, v237
	v_xor_b32_e32 v237, v237, v115
	ds_read_b128 v[124:127], v237
	v_lshlrev_b32_e32 v76, 16, v32
	v_and_b32_e32 v77, 0xffff0000, v32
	v_lshlrev_b32_e32 v78, 16, v33
	s_waitcnt lgkmcnt(1)
	v_sub_f32_e32 v0, v96, v116
	v_mul_f32_e32 v0, 0x3fb8aa3b, v0
	v_exp_f32_e32 v96, v0
	v_sub_f32_e32 v0, v97, v117
	v_mul_f32_e32 v0, 0x3fb8aa3b, v0
	v_exp_f32_e32 v97, v0
	v_sub_f32_e32 v0, v98, v118
	v_mul_f32_e32 v0, 0x3fb8aa3b, v0
	v_exp_f32_e32 v98, v0
	v_sub_f32_e32 v0, v99, v119
	v_mul_f32_e32 v0, 0x3fb8aa3b, v0
	v_exp_f32_e32 v99, v0
	s_waitcnt lgkmcnt(0)
	v_sub_f32_e32 v0, v120, v124
	v_mul_f32_e32 v0, 0x3fb8aa3b, v0
	v_exp_f32_e32 v100, v0
	v_sub_f32_e32 v0, v121, v125
	v_mul_f32_e32 v0, 0x3fb8aa3b, v0
	v_exp_f32_e32 v101, v0
	v_sub_f32_e32 v0, v122, v126
	v_mul_f32_e32 v0, 0x3fb8aa3b, v0
	v_exp_f32_e32 v112, v0
	v_sub_f32_e32 v0, v123, v127
	v_mul_f32_e32 v0, 0x3fb8aa3b, v0
	v_exp_f32_e32 v113, v0
	v_and_b32_e32 v79, 0xffff0000, v33
	v_lshlrev_b32_e32 v80, 16, v34
	v_and_b32_e32 v81, 0xffff0000, v34
	v_lshlrev_b32_e32 v90, 16, v35
	v_and_b32_e32 v91, 0xffff0000, v35
	v_pk_mul_f32 v[96:97], v[96:97], v[76:77]
	v_pk_mul_f32 v[98:99], v[98:99], v[78:79]
	v_pk_mul_f32 v[100:101], v[100:101], v[80:81]
	v_pk_mul_f32 v[112:113], v[112:113], v[90:91]
	s_lshl_b32 s72, s64, 9
	v_cmp_gt_i32_e64 s[12:13], s53, v2
	v_cvt_pk_bf16_f32 v96, v96, v97
	v_cvt_pk_bf16_f32 v97, v98, v99
	v_cvt_pk_bf16_f32 v98, v100, v101
	v_cvt_pk_bf16_f32 v99, v112, v113
	v_lshl_add_u32 v111, v2, 2, 0
	ds_write_b128 v109, v[96:99] offset:41984
	s_and_saveexec_b64 s[62:63], s[12:13]
	s_cbranch_execz .LBB0_1455
	v_xor_b32_e32 v236, 48, v111
	ds_read_b32 v0, v236 offset:32256
	s_ashr_i32 s57, s56, 31
	s_lshl_b64 s[74:75], s[56:57], 15
	s_add_u32 s26, s0, s74
	s_addc_u32 s57, s1, s75
	s_waitcnt lgkmcnt(0)
	v_mul_f32_e32 v0, 0x3fb8aa3b, v0
	v_exp_f32_e32 v0, v0
	s_add_u32 s74, s26, s72
	s_addc_u32 s75, s57, 0
	v_lshl_add_u64 v[96:97], v[2:3], 2, s[74:75]
	global_store_dword v[96:97], v0, off

.LBB0_1463:
	v_mfma_f32_16x16x32_bf16 v[72:75], v[56:59], v[72:75], 0
	v_or_b32_e32 v93, 0x200, v105
	v_or_b32_e32 v118, 0x400, v105
	v_or_b32_e32 v119, 0x600, v105
	v_mfma_f32_16x16x32_bf16 v[68:71], v[56:59], v[68:71], 0
	v_or_b32_e32 v120, 0x800, v105
	s_waitcnt vmcnt(8)
	s_nop 1
	v_add_f32_e32 v132, v64, v72
	v_add_f32_e32 v73, v65, v73
	v_min_f32_e32 v72, 0, v132
	v_mul_f32_e64 v132, |v132|, s49
	v_mul_f32_e64 v133, |v73|, s49
	v_add_f32_e32 v134, v66, v74
	v_add_f32_e32 v75, v67, v75
	v_exp_f32_e32 v132, v132
	v_exp_f32_e32 v133, v133
	v_min_f32_e32 v74, 0, v134
	v_mul_f32_e64 v134, |v134|, s49
	v_mul_f32_e64 v135, |v75|, s49
	v_exp_f32_e32 v134, v134
	v_exp_f32_e32 v135, v135
	v_add_f32_e32 v132, 1.0, v132
	v_add_f32_e32 v133, 1.0, v133
	v_log_f32_e32 v132, v132
	v_log_f32_e32 v133, v133
	v_add_f32_e32 v134, 1.0, v134
	v_add_f32_e32 v135, 1.0, v135
	v_log_f32_e32 v134, v134
	v_log_f32_e32 v135, v135
	v_min_f32_e32 v73, 0, v73
	v_xor_b32_e32 v133, 0x80000000, v133
	v_xor_b32_e32 v132, 0x80000000, v132
	v_min_f32_e32 v75, 0, v75
	v_pk_fma_f32 v[72:73], v[132:133], s[52:53], v[72:73] op_sel_hi:[1,0,1]
	v_xor_b32_e32 v133, 0x80000000, v135
	v_xor_b32_e32 v132, 0x80000000, v134
	v_pk_fma_f32 v[74:75], v[132:133], s[52:53], v[74:75] op_sel_hi:[1,0,1]
	v_pk_mul_f32 v[72:73], v[72:73], s[54:55] op_sel_hi:[1,0]
	v_pk_mul_f32 v[74:75], v[74:75], s[54:55] op_sel_hi:[1,0]
	v_lshlrev_b32_e32 v237, 3, v204
	v_and_b32_e32 v237, 0x30, v237
	v_xor_b32_e32 v237, v237, v108
	ds_write_b128 v237, v[72:75]
	v_add_f32_e32 v72, v64, v68
	v_add_f32_e32 v69, v65, v69
	v_min_f32_e32 v68, 0, v72
	v_mul_f32_e64 v72, |v72|, s49
	v_mul_f32_e64 v73, |v69|, s49
	v_add_f32_e32 v74, v66, v70
	v_add_f32_e32 v71, v67, v71
	v_exp_f32_e32 v72, v72
	v_exp_f32_e32 v73, v73
	v_min_f32_e32 v70, 0, v74
	v_mul_f32_e64 v74, |v74|, s49
	v_mul_f32_e64 v75, |v71|, s49
	v_exp_f32_e32 v74, v74
	v_exp_f32_e32 v75, v75
	v_add_f32_e32 v72, 1.0, v72
	v_add_f32_e32 v73, 1.0, v73
	v_log_f32_e32 v72, v72
	v_log_f32_e32 v73, v73
	v_add_f32_e32 v74, 1.0, v74
	v_add_f32_e32 v75, 1.0, v75
	v_log_f32_e32 v74, v74
	v_log_f32_e32 v75, v75
	v_mfma_f32_16x16x32_bf16 v[52:55], v[56:59], v[52:55], 0
	v_min_f32_e32 v69, 0, v69
	v_xor_b32_e32 v73, 0x80000000, v73
	v_xor_b32_e32 v72, 0x80000000, v72
	v_mfma_f32_16x16x32_bf16 v[60:63], v[56:59], v[60:63], 0
	v_min_f32_e32 v71, 0, v71
	v_pk_fma_f32 v[68:69], v[72:73], s[52:53], v[68:69] op_sel_hi:[1,0,1]
	v_xor_b32_e32 v73, 0x80000000, v75
	v_xor_b32_e32 v72, 0x80000000, v74
	v_pk_fma_f32 v[70:71], v[72:73], s[52:53], v[70:71] op_sel_hi:[1,0,1]
	v_pk_mul_f32 v[68:69], v[68:69], s[54:55] op_sel_hi:[1,0]
	v_pk_mul_f32 v[70:71], v[70:71], s[54:55] op_sel_hi:[1,0]
	v_add_f32_e32 v56, v64, v52
	v_add_f32_e32 v53, v65, v53
	v_lshlrev_b32_e32 v236, 3, v204
	v_and_b32_e32 v236, 0x30, v236
	v_xor_b32_e32 v236, v236, v108
	ds_write_b128 v236, v[68:71] offset:8192
	v_add_f32_e32 v68, v64, v60
	v_add_f32_e32 v61, v65, v61
	v_min_f32_e32 v52, 0, v56
	v_mul_f32_e64 v56, |v56|, s49
	v_mul_f32_e64 v57, |v53|, s49
	v_add_f32_e32 v58, v66, v54
	v_add_f32_e32 v55, v67, v55
	v_min_f32_e32 v60, 0, v68
	v_mul_f32_e64 v68, |v68|, s49
	v_mul_f32_e64 v69, |v61|, s49
	v_add_f32_e32 v70, v66, v62
	v_add_f32_e32 v63, v67, v63
	v_exp_f32_e32 v56, v56
	v_exp_f32_e32 v57, v57
	v_min_f32_e32 v54, 0, v58
	v_mul_f32_e64 v58, |v58|, s49
	v_mul_f32_e64 v59, |v55|, s49
	v_exp_f32_e32 v68, v68
	v_exp_f32_e32 v69, v69
	v_min_f32_e32 v62, 0, v70
	v_mul_f32_e64 v70, |v70|, s49
	v_mul_f32_e64 v71, |v63|, s49
	v_exp_f32_e32 v58, v58
	v_exp_f32_e32 v59, v59
	v_exp_f32_e32 v70, v70
	v_exp_f32_e32 v71, v71
	v_add_f32_e32 v56, 1.0, v56
	v_add_f32_e32 v57, 1.0, v57
	v_add_f32_e32 v68, 1.0, v68
	v_add_f32_e32 v69, 1.0, v69
	v_log_f32_e32 v56, v56
	v_log_f32_e32 v57, v57
	v_add_f32_e32 v58, 1.0, v58
	v_add_f32_e32 v59, 1.0, v59
	v_log_f32_e32 v68, v68
	v_log_f32_e32 v69, v69
	v_add_f32_e32 v70, 1.0, v70
	v_add_f32_e32 v71, 1.0, v71
	v_log_f32_e32 v58, v58
	v_log_f32_e32 v59, v59
	v_log_f32_e32 v70, v70
	v_log_f32_e32 v71, v71
	v_min_f32_e32 v53, 0, v53
	v_xor_b32_e32 v57, 0x80000000, v57
	v_xor_b32_e32 v56, 0x80000000, v56
	v_min_f32_e32 v61, 0, v61
	v_xor_b32_e32 v69, 0x80000000, v69
	v_xor_b32_e32 v68, 0x80000000, v68
	v_min_f32_e32 v55, 0, v55
	v_pk_fma_f32 v[52:53], v[56:57], s[52:53], v[52:53] op_sel_hi:[1,0,1]
	v_xor_b32_e32 v57, 0x80000000, v59
	v_xor_b32_e32 v56, 0x80000000, v58
	v_min_f32_e32 v63, 0, v63
	v_pk_fma_f32 v[60:61], v[68:69], s[52:53], v[60:61] op_sel_hi:[1,0,1]
	v_xor_b32_e32 v69, 0x80000000, v71
	v_xor_b32_e32 v68, 0x80000000, v70
	v_pk_fma_f32 v[54:55], v[56:57], s[52:53], v[54:55] op_sel_hi:[1,0,1]
	v_or_b32_e32 v121, 0xa00, v105
	v_or_b32_e32 v122, 0xc00, v105
	v_or_b32_e32 v123, 0xe00, v105
	v_pk_fma_f32 v[62:63], v[68:69], s[52:53], v[62:63] op_sel_hi:[1,0,1]
	v_pk_mul_f32 v[54:55], v[54:55], s[54:55] op_sel_hi:[1,0]
	v_pk_mul_f32 v[52:53], v[52:53], s[54:55] op_sel_hi:[1,0]
	v_or_b32_e32 v124, 0x1000, v105
	v_or_b32_e32 v131, 0x1e00, v105
	v_pk_mul_f32 v[62:63], v[62:63], s[54:55] op_sel_hi:[1,0]
	v_pk_mul_f32 v[60:61], v[60:61], s[54:55] op_sel_hi:[1,0]
	v_lshlrev_b32_e32 v237, 3, v204
	v_and_b32_e32 v237, 0x30, v237
	v_xor_b32_e32 v237, v237, v108
	ds_write_b128 v237, v[52:55] offset:24576
	v_sub_u32_e32 v52, v104, v105
	v_sub_u32_e32 v53, v104, v93
	v_sub_u32_e32 v54, v104, v118
	v_sub_u32_e32 v55, v104, v119
	v_sub_u32_e32 v56, v104, v120
	v_sub_u32_e32 v57, v104, v121
	v_sub_u32_e32 v58, v104, v122
	v_sub_u32_e32 v59, v104, v123
	v_or_b32_e32 v125, 0x1200, v105
	v_or_b32_e32 v126, 0x1400, v105
	v_or_b32_e32 v127, 0x1600, v105
	v_or_b32_e32 v128, 0x1800, v105
	v_or_b32_e32 v129, 0x1a00, v105
	v_or_b32_e32 v130, 0x1c00, v105
	v_lshlrev_b32_e32 v236, 3, v204
	v_and_b32_e32 v236, 0x30, v236
	v_xor_b32_e32 v236, v236, v108
	ds_write_b128 v236, v[60:63] offset:16384
	s_waitcnt lgkmcnt(0)
	s_barrier
	v_xor_b32_e32 v237, 48, v52
	ds_read_b32 v52, v237 offset:32256
	v_xor_b32_e32 v236, 48, v53
	ds_read_b32 v53, v236 offset:32256
	v_xor_b32_e32 v237, 32, v54
	ds_read_b32 v54, v237 offset:32256
	v_xor_b32_e32 v236, 32, v55
	ds_read_b32 v55, v236 offset:32256
	v_xor_b32_e32 v237, 16, v56
	ds_read_b32 v56, v237 offset:32256
	v_xor_b32_e32 v236, 16, v57
	ds_read_b32 v57, v236 offset:32256
	ds_read_b32 v58, v58 offset:32256
	ds_read_b32 v59, v59 offset:32256
	v_sub_u32_e32 v60, v104, v124
	v_sub_u32_e32 v67, v104, v131
	s_waitcnt lgkmcnt(7)
	v_add_f32_e32 v68, 0, v52
	v_sub_u32_e32 v61, v104, v125
	v_sub_u32_e32 v62, v104, v126
	v_sub_u32_e32 v63, v104, v127
	v_sub_u32_e32 v64, v104, v128
	v_sub_u32_e32 v65, v104, v129
	v_sub_u32_e32 v66, v104, v130
	v_xor_b32_e32 v237, 48, v60
	ds_read_b32 v60, v237 offset:32256
	v_xor_b32_e32 v236, 48, v61
	ds_read_b32 v69, v236 offset:32256
	v_xor_b32_e32 v237, 32, v62
	ds_read_b32 v70, v237 offset:32256
	v_xor_b32_e32 v236, 32, v63
	ds_read_b32 v71, v236 offset:32256
	v_xor_b32_e32 v237, 16, v64
	ds_read_b32 v72, v237 offset:32256
	v_xor_b32_e32 v236, 16, v65
	ds_read_b32 v73, v236 offset:32256
	ds_read_b32 v74, v66 offset:32256
	ds_read_b32 v75, v67 offset:32256
	s_waitcnt lgkmcnt(14)
	v_add_f32_e32 v67, v68, v53
	s_waitcnt lgkmcnt(13)
	v_add_f32_e32 v66, v67, v54
	s_waitcnt lgkmcnt(12)
	v_add_f32_e32 v65, v66, v55
	s_waitcnt lgkmcnt(11)
	v_add_f32_e32 v64, v65, v56
	s_waitcnt lgkmcnt(10)
	v_add_f32_e32 v63, v64, v57
	s_waitcnt lgkmcnt(9)
	v_add_f32_e32 v62, v63, v58
	s_waitcnt lgkmcnt(8)
	v_add_f32_e32 v61, v62, v59
	s_waitcnt lgkmcnt(7)
	v_add_f32_e32 v60, v61, v60
	s_waitcnt lgkmcnt(6)
	v_add_f32_e32 v59, v60, v69
	s_waitcnt lgkmcnt(5)
	v_add_f32_e32 v58, v59, v70
	s_waitcnt lgkmcnt(4)
	v_add_f32_e32 v57, v58, v71
	s_waitcnt lgkmcnt(3)
	v_add_f32_e32 v55, v57, v72
	s_waitcnt lgkmcnt(2)
	v_add_f32_e32 v54, v55, v73
	s_waitcnt lgkmcnt(1)
	v_add_f32_e32 v53, v54, v74
	s_waitcnt lgkmcnt(0)
	v_add_f32_e32 v52, v53, v75
	v_mov_b32_e32 v56, 0
	ds_write_b32 v107, v52
	s_waitcnt lgkmcnt(0)
	s_barrier
	s_and_saveexec_b64 s[56:57], s[10:11]
	s_cbranch_execnz .LBB0_1506
	s_or_b64 exec, exec, s[56:57]
	s_and_saveexec_b64 s[10:11], s[14:15]
	s_cbranch_execnz .LBB0_1507

.LBB0_1467:
	s_or_b64 exec, exec, s[10:11]
	v_sub_u32_e32 v69, 0, v105
	v_sub_u32_e32 v70, 0, v93
	v_add_f32_e32 v68, v68, v56
	v_add_u32_e32 v69, v104, v69
	v_sub_u32_e32 v71, 0, v118
	v_xor_b32_e32 v237, 48, v69
	ds_write_b32 v237, v68 offset:32256
	v_add_f32_e32 v67, v67, v56
	v_add_u32_e32 v68, v104, v70
	v_sub_u32_e32 v72, 0, v119
	v_xor_b32_e32 v236, 48, v68
	ds_write_b32 v236, v67 offset:32256
	v_add_f32_e32 v66, v66, v56
	v_add_u32_e32 v67, v104, v71
	v_sub_u32_e32 v73, 0, v120
	v_xor_b32_e32 v237, 32, v67
	ds_write_b32 v237, v66 offset:32256
	v_add_f32_e32 v65, v65, v56
	v_add_u32_e32 v66, v104, v72
	v_sub_u32_e32 v74, 0, v121
	v_xor_b32_e32 v236, 32, v66
	ds_write_b32 v236, v65 offset:32256
	v_add_f32_e32 v64, v64, v56
	v_add_u32_e32 v65, v104, v73
	v_sub_u32_e32 v75, 0, v122
	v_xor_b32_e32 v237, 16, v65
	ds_write_b32 v237, v64 offset:32256
	v_add_f32_e32 v63, v63, v56
	v_add_u32_e32 v64, v104, v74
	v_sub_u32_e32 v93, 0, v123
	v_xor_b32_e32 v236, 16, v64
	ds_write_b32 v236, v63 offset:32256
	v_add_f32_e32 v62, v62, v56
	v_add_u32_e32 v63, v104, v75
	v_sub_u32_e32 v105, 0, v124
	ds_write_b32 v63, v62 offset:32256
	v_add_f32_e32 v61, v61, v56
	v_add_u32_e32 v62, v104, v93
	v_sub_u32_e32 v106, 0, v125
	ds_write_b32 v62, v61 offset:32256
	v_add_f32_e32 v60, v60, v56
	v_add_u32_e32 v61, v104, v105
	v_sub_u32_e32 v107, 0, v126
	v_xor_b32_e32 v237, 48, v61
	ds_write_b32 v237, v60 offset:32256
	v_add_f32_e32 v59, v59, v56
	v_add_u32_e32 v60, v104, v106
	v_sub_u32_e32 v108, 0, v127
	v_xor_b32_e32 v236, 48, v60
	ds_write_b32 v236, v59 offset:32256
	v_add_f32_e32 v58, v58, v56
	v_add_u32_e32 v59, v104, v107
	v_sub_u32_e32 v118, 0, v128
	v_xor_b32_e32 v237, 32, v59
	ds_write_b32 v237, v58 offset:32256
	v_add_f32_e32 v57, v57, v56
	v_add_u32_e32 v58, v104, v108
	v_sub_u32_e32 v119, 0, v129
	v_xor_b32_e32 v236, 32, v58
	ds_write_b32 v236, v57 offset:32256
	v_add_f32_e32 v55, v55, v56
	v_add_u32_e32 v57, v104, v118
	v_sub_u32_e32 v120, 0, v130
	v_xor_b32_e32 v237, 16, v57
	ds_write_b32 v237, v55 offset:32256
	v_add_f32_e32 v54, v54, v56
	v_add_u32_e32 v55, v104, v119
	v_sub_u32_e32 v121, 0, v131
	v_xor_b32_e32 v236, 16, v55
	ds_write_b32 v236, v54 offset:32256
	v_add_f32_e32 v53, v53, v56
	v_add_u32_e32 v54, v104, v120
	ds_write_b32 v54, v53 offset:32256
	v_add_f32_e32 v52, v52, v56
	v_add_u32_e32 v53, v104, v121
	ds_write_b32 v53, v52 offset:32256
	s_waitcnt lgkmcnt(0)
	s_barrier
	v_lshrrev_b32_e32 v237, 1, v204
	v_and_b32_e32 v237, 0x30, v237
	v_xor_b32_e32 v237, v237, v114
	ds_read_b128 v[52:55], v237
	ds_read_b128 v[56:59], v110
	v_xor_b32_e32 v236, 16, v110
	ds_read_b128 v[60:63], v236
	v_lshrrev_b32_e32 v237, 1, v204
	v_and_b32_e32 v237, 0x30, v237
	v_xor_b32_e32 v237, 16, v237
	v_xor_b32_e32 v237, v237, v114
	ds_read_b128 v[64:67], v237
	s_waitcnt lgkmcnt(2)
	v_sub_f32_e32 v52, v56, v52
	v_sub_f32_e32 v53, v57, v53
	v_sub_f32_e32 v54, v58, v54
	v_sub_f32_e32 v55, v59, v55
	s_waitcnt lgkmcnt(0)
	v_sub_f32_e32 v64, v60, v64
	v_sub_f32_e32 v65, v61, v65
	v_sub_f32_e32 v66, v62, v66
	v_sub_f32_e32 v67, v63, v67
	v_mul_f32_e32 v52, 0x3fb8aa3b, v52
	v_mul_f32_e32 v53, 0x3fb8aa3b, v53
	v_mul_f32_e32 v54, 0x3fb8aa3b, v54
	v_mul_f32_e32 v55, 0x3fb8aa3b, v55
	v_mul_f32_e32 v64, 0x3fb8aa3b, v64
	v_mul_f32_e32 v65, 0x3fb8aa3b, v65
	v_mul_f32_e32 v66, 0x3fb8aa3b, v66
	v_mul_f32_e32 v67, 0x3fb8aa3b, v67
	v_exp_f32_e32 v52, v52
	v_exp_f32_e32 v53, v53
	v_exp_f32_e32 v54, v54
	v_exp_f32_e32 v55, v55
	v_exp_f32_e32 v64, v64
	v_exp_f32_e32 v65, v65
	v_exp_f32_e32 v66, v66
	v_exp_f32_e32 v67, v67
	v_pk_mul_f32 v[52:53], v[52:53], v[82:83]
	v_pk_mul_f32 v[54:55], v[54:55], v[84:85]
	v_pk_mul_f32 v[64:65], v[64:65], v[86:87]
	v_pk_mul_f32 v[66:67], v[66:67], v[88:89]
	v_cvt_pk_bf16_f32 v52, v52, v53
	v_cvt_pk_bf16_f32 v53, v54, v55
	v_cvt_pk_bf16_f32 v54, v64, v65
	v_cvt_pk_bf16_f32 v55, v66, v67
	ds_write_b128 v109, v[52:55] offset:32768
	v_lshrrev_b32_e32 v236, 1, v204
	v_and_b32_e32 v236, 0x30, v236
	v_xor_b32_e32 v236, v236, v115
	ds_read_b128 v[52:55], v236
	v_lshrrev_b32_e32 v237, 1, v204
	v_and_b32_e32 v237, 0x30, v237
	v_xor_b32_e32 v237, 16, v237
	v_xor_b32_e32 v237, v237, v115
	ds_read_b128 v[64:67], v237
	s_waitcnt lgkmcnt(1)
	v_sub_f32_e32 v52, v56, v52
	v_sub_f32_e32 v53, v57, v53
	v_sub_f32_e32 v54, v58, v54
	v_sub_f32_e32 v55, v59, v55
	s_waitcnt lgkmcnt(0)
	v_sub_f32_e32 v56, v60, v64
	v_sub_f32_e32 v57, v61, v65
	v_sub_f32_e32 v58, v62, v66
	v_sub_f32_e32 v59, v63, v67
	v_mul_f32_e32 v52, 0x3fb8aa3b, v52
	v_mul_f32_e32 v53, 0x3fb8aa3b, v53
	v_mul_f32_e32 v54, 0x3fb8aa3b, v54
	v_mul_f32_e32 v55, 0x3fb8aa3b, v55
	v_mul_f32_e32 v56, 0x3fb8aa3b, v56
	v_mul_f32_e32 v57, 0x3fb8aa3b, v57
	v_mul_f32_e32 v58, 0x3fb8aa3b, v58
	v_mul_f32_e32 v59, 0x3fb8aa3b, v59
	v_exp_f32_e32 v52, v52
	v_exp_f32_e32 v53, v53
	v_exp_f32_e32 v54, v54
	v_exp_f32_e32 v55, v55
	v_exp_f32_e32 v56, v56
	v_exp_f32_e32 v57, v57
	v_exp_f32_e32 v58, v58
	v_exp_f32_e32 v59, v59
	v_pk_mul_f32 v[52:53], v[52:53], v[76:77]
	v_pk_mul_f32 v[54:55], v[54:55], v[78:79]
	v_pk_mul_f32 v[56:57], v[56:57], v[80:81]
	v_pk_mul_f32 v[58:59], v[58:59], v[90:91]
	v_cvt_pk_bf16_f32 v52, v52, v53
	v_cvt_pk_bf16_f32 v53, v54, v55
	v_cvt_pk_bf16_f32 v54, v56, v57
	v_cvt_pk_bf16_f32 v55, v58, v59
	ds_write_b128 v109, v[52:55] offset:41984
	s_and_saveexec_b64 s[10:11], s[12:13]
	s_cbranch_execz .LBB0_1469
	v_lshrrev_b32_e32 v236, 4, v204
	v_and_b32_e32 v236, 0x30, v236
	v_xor_b32_e32 v236, v236, v111
	ds_read_b32 v52, v236
	s_ashr_i32 s63, s62, 31
	s_lshl_b64 s[12:13], s[62:63], 15
	s_add_u32 s12, s0, s12
	s_addc_u32 s13, s1, s13
	s_waitcnt lgkmcnt(0)
	v_mul_f32_e32 v52, 0x3fb8aa3b, v52
	v_exp_f32_e32 v52, v52
	s_add_u32 s12, s12, s72
	s_addc_u32 s13, s13, 0
	v_lshl_add_u64 v[2:3], v[2:3], 2, s[12:13]
	global_store_dword v[2:3], v52, off

.LBB0_1484:
	v_lshlrev_b32_e32 v86, 2, v2
	v_and_b32_e32 v87, 0x1fc, v86
	v_add_u32_e32 v104, 0, v87
	v_add_u32_e32 v107, s92, v86
	v_add_u32_e32 v106, s92, v87
	s_nop 0
	v_mfma_f32_16x16x32_bf16 v[86:89], v[76:79], v[72:75], 0
	v_lshlrev_b32_e32 v84, 9, v92
	v_and_b32_e32 v85, 0xffffffc0, v2
	v_add3_u32 v85, 0, v84, v85
	v_add_u32_e32 v108, v85, v0
	v_ashrrev_i32_e32 v84, 7, v2
	s_nop 0
	s_nop 1
	v_add_f32_e32 v90, v80, v86
	v_add_f32_e32 v87, v81, v87
	v_min_f32_e32 v86, 0, v90
	v_mul_f32_e64 v90, |v90|, s49
	v_mul_f32_e64 v91, |v87|, s49
	v_add_f32_e32 v95, v82, v88
	v_add_f32_e32 v89, v83, v89
	v_exp_f32_e32 v90, v90
	v_exp_f32_e32 v91, v91
	v_min_f32_e32 v88, 0, v95
	v_mul_f32_e64 v95, |v95|, s49
	v_mul_f32_e64 v96, |v89|, s49
	v_exp_f32_e32 v95, v95
	v_exp_f32_e32 v96, v96
	v_add_f32_e32 v90, 1.0, v90
	v_add_f32_e32 v91, 1.0, v91
	v_log_f32_e32 v90, v90
	v_log_f32_e32 v91, v91
	v_add_f32_e32 v95, 1.0, v95
	v_add_f32_e32 v96, 1.0, v96
	v_log_f32_e32 v95, v95
	v_log_f32_e32 v96, v96
	v_min_f32_e32 v87, 0, v87
	v_xor_b32_e32 v91, 0x80000000, v91
	v_xor_b32_e32 v90, 0x80000000, v90
	v_min_f32_e32 v89, 0, v89
	v_pk_fma_f32 v[86:87], v[90:91], s[52:53], v[86:87] op_sel_hi:[1,0,1]
	v_xor_b32_e32 v91, 0x80000000, v96
	v_xor_b32_e32 v90, 0x80000000, v95
	v_pk_fma_f32 v[88:89], v[90:91], s[52:53], v[88:89] op_sel_hi:[1,0,1]
	v_pk_mul_f32 v[86:87], v[86:87], s[54:55] op_sel_hi:[1,0]
	v_pk_mul_f32 v[88:89], v[88:89], s[54:55] op_sel_hi:[1,0]
	v_lshlrev_b32_e32 v237, 3, v204
	v_and_b32_e32 v237, 0x30, v237
	v_xor_b32_e32 v237, v237, v108
	ds_write_b128 v237, v[86:89]
	v_mfma_f32_16x16x32_bf16 v[86:89], v[76:79], v[68:71], 0
	v_lshlrev_b32_e32 v105, 13, v84
	v_cmp_lt_i32_e64 s[10:11], 0, v84
	v_mov_b32_e32 v117, 0
	s_nop 4
	v_add_f32_e32 v85, v81, v87
	v_mul_f32_e64 v87, |v85|, s49
	v_exp_f32_e32 v90, v87
	v_add_f32_e32 v0, v80, v86
	v_min_f32_e32 v87, 0, v85
	v_min_f32_e32 v86, 0, v0
	v_add_f32_e32 v85, 1.0, v90
	v_add_f32_e32 v90, v82, v88
	v_mul_f32_e64 v0, |v0|, s49
	v_min_f32_e32 v88, 0, v90
	v_mul_f32_e64 v90, |v90|, s49
	v_add_f32_e32 v89, v83, v89
	v_exp_f32_e32 v0, v0
	v_exp_f32_e32 v90, v90
	v_mul_f32_e64 v91, |v89|, s49
	v_exp_f32_e32 v91, v91
	v_add_f32_e32 v0, 1.0, v0
	v_add_f32_e32 v90, 1.0, v90
	v_log_f32_e32 v0, v0
	v_log_f32_e32 v85, v85
	v_log_f32_e32 v95, v90
	v_add_f32_e32 v90, 1.0, v91
	v_log_f32_e32 v96, v90
	v_xor_b32_e32 v91, 0x80000000, v85
	v_xor_b32_e32 v90, 0x80000000, v0
	v_min_f32_e32 v89, 0, v89
	v_pk_fma_f32 v[86:87], v[90:91], s[52:53], v[86:87] op_sel_hi:[1,0,1]
	v_xor_b32_e32 v91, 0x80000000, v96
	v_xor_b32_e32 v90, 0x80000000, v95
	v_pk_fma_f32 v[88:89], v[90:91], s[52:53], v[88:89] op_sel_hi:[1,0,1]
	v_pk_mul_f32 v[86:87], v[86:87], s[54:55] op_sel_hi:[1,0]
	v_pk_mul_f32 v[88:89], v[88:89], s[54:55] op_sel_hi:[1,0]
	v_lshlrev_b32_e32 v236, 3, v204
	v_and_b32_e32 v236, 0x30, v236
	v_xor_b32_e32 v236, v236, v108
	ds_write_b128 v236, v[86:89] offset:8192
	v_mfma_f32_16x16x32_bf16 v[86:89], v[76:79], v[60:63], 0
	v_mfma_f32_16x16x32_bf16 v[76:79], v[76:79], v[52:55], 0
	s_nop 6
	v_add_f32_e32 v85, v81, v87
	v_mul_f32_e64 v87, |v85|, s49
	v_exp_f32_e32 v90, v87
	v_add_f32_e32 v0, v80, v86
	v_min_f32_e32 v86, 0, v0
	v_mul_f32_e64 v0, |v0|, s49
	v_exp_f32_e32 v0, v0
	v_min_f32_e32 v87, 0, v85
	v_add_f32_e32 v85, 1.0, v90
	v_add_f32_e32 v90, v82, v88
	v_min_f32_e32 v88, 0, v90
	v_mul_f32_e64 v90, |v90|, s49
	v_add_f32_e32 v89, v83, v89
	v_exp_f32_e32 v90, v90
	v_mul_f32_e64 v91, |v89|, s49
	v_add_f32_e32 v0, 1.0, v0
	v_exp_f32_e32 v91, v91
	v_log_f32_e32 v0, v0
	v_add_f32_e32 v90, 1.0, v90
	v_log_f32_e32 v95, v90
	v_add_f32_e32 v90, 1.0, v91
	v_log_f32_e32 v96, v90
	v_xor_b32_e32 v90, 0x80000000, v0
	v_add_f32_e32 v0, v80, v76
	v_add_f32_e32 v77, v81, v77
	v_add_f32_e32 v81, v82, v78
	v_min_f32_e32 v76, 0, v0
	v_mul_f32_e64 v0, |v0|, s49
	v_mul_f32_e64 v80, |v77|, s49
	v_min_f32_e32 v78, 0, v81
	v_mul_f32_e64 v81, |v81|, s49
	v_add_f32_e32 v79, v83, v79
	v_exp_f32_e32 v0, v0
	v_exp_f32_e32 v80, v80
	v_exp_f32_e32 v81, v81
	v_mul_f32_e64 v82, |v79|, s49
	v_exp_f32_e32 v82, v82
	v_add_f32_e32 v0, 1.0, v0
	v_add_f32_e32 v80, 1.0, v80
	v_add_f32_e32 v81, 1.0, v81
	v_log_f32_e32 v85, v85
	v_log_f32_e32 v0, v0
	v_log_f32_e32 v80, v80
	v_log_f32_e32 v83, v81
	v_add_f32_e32 v81, 1.0, v82
	v_log_f32_e32 v82, v81
	v_xor_b32_e32 v91, 0x80000000, v85
	v_min_f32_e32 v77, 0, v77
	v_xor_b32_e32 v81, 0x80000000, v80
	v_xor_b32_e32 v80, 0x80000000, v0
	v_min_f32_e32 v89, 0, v89
	v_pk_fma_f32 v[86:87], v[90:91], s[52:53], v[86:87] op_sel_hi:[1,0,1]
	v_xor_b32_e32 v91, 0x80000000, v96
	v_xor_b32_e32 v90, 0x80000000, v95
	v_min_f32_e32 v79, 0, v79
	v_pk_fma_f32 v[76:77], v[80:81], s[52:53], v[76:77] op_sel_hi:[1,0,1]
	v_xor_b32_e32 v81, 0x80000000, v82
	v_xor_b32_e32 v80, 0x80000000, v83
	v_pk_fma_f32 v[88:89], v[90:91], s[52:53], v[88:89] op_sel_hi:[1,0,1]
	v_pk_fma_f32 v[78:79], v[80:81], s[52:53], v[78:79] op_sel_hi:[1,0,1]
	v_pk_mul_f32 v[88:89], v[88:89], s[54:55] op_sel_hi:[1,0]
	v_pk_mul_f32 v[86:87], v[86:87], s[54:55] op_sel_hi:[1,0]
	v_pk_mul_f32 v[78:79], v[78:79], s[54:55] op_sel_hi:[1,0]
	v_pk_mul_f32 v[76:77], v[76:77], s[54:55] op_sel_hi:[1,0]
	v_add_u32_e32 v0, v104, v105
	v_lshlrev_b32_e32 v237, 3, v204
	v_and_b32_e32 v237, 0x30, v237
	v_xor_b32_e32 v237, v237, v108
	ds_write_b128 v237, v[86:89] offset:16384
	v_lshlrev_b32_e32 v236, 3, v204
	v_and_b32_e32 v236, 0x30, v236
	v_xor_b32_e32 v236, v236, v108
	ds_write_b128 v236, v[76:79] offset:24576
	s_waitcnt lgkmcnt(0)
	s_barrier
	ds_read2st64_b32 v[76:77], v0 offset1:2
	v_xor_b32_e32 v237, 16, v0
	ds_read2st64_b32 v[78:79], v237 offset0:4 offset1:6
	v_xor_b32_e32 v236, 32, v0
	ds_read2st64_b32 v[80:81], v236 offset0:8 offset1:10
	v_xor_b32_e32 v237, 48, v0
	ds_read2st64_b32 v[82:83], v237 offset0:12 offset1:14
	ds_read2st64_b32 v[86:87], v0 offset0:16 offset1:18
	v_xor_b32_e32 v236, 16, v0
	ds_read2st64_b32 v[88:89], v236 offset0:20 offset1:22
	v_xor_b32_e32 v237, 32, v0
	ds_read2st64_b32 v[90:91], v237 offset0:24 offset1:26
	v_xor_b32_e32 v236, 48, v0
	ds_read2st64_b32 v[118:119], v236 offset0:28 offset1:30
	s_waitcnt lgkmcnt(7)
	v_add_f32_e32 v115, 0, v76
	v_add_f32_e32 v116, v115, v77
	s_waitcnt lgkmcnt(6)
	v_add_f32_e32 v113, v116, v78
	v_add_f32_e32 v114, v113, v79
	s_waitcnt lgkmcnt(5)
	v_add_f32_e32 v111, v114, v80
	v_add_f32_e32 v112, v111, v81
	s_waitcnt lgkmcnt(4)
	v_add_f32_e32 v101, v112, v82
	v_add_f32_e32 v109, v101, v83
	s_waitcnt lgkmcnt(3)
	v_add_f32_e32 v99, v109, v86
	v_add_f32_e32 v100, v99, v87
	s_waitcnt lgkmcnt(2)
	v_add_f32_e32 v97, v100, v88
	v_add_f32_e32 v98, v97, v89
	s_waitcnt lgkmcnt(1)
	v_add_f32_e32 v95, v98, v90
	v_add_f32_e32 v96, v95, v91
	s_waitcnt lgkmcnt(0)
	v_add_f32_e32 v90, v96, v118
	v_add_f32_e32 v91, v90, v119
	ds_write_b32 v107, v91
	s_waitcnt lgkmcnt(0)
	s_barrier
	s_and_saveexec_b64 s[12:13], s[10:11]
	s_cbranch_execnz .LBB0_1508
	s_or_b64 exec, exec, s[12:13]
	v_cmp_lt_i32_e64 s[14:15], 1, v84
	s_and_saveexec_b64 s[12:13], s[14:15]
	s_cbranch_execnz .LBB0_1509

.LBB0_1488:
	s_or_b64 exec, exec, s[12:13]
	v_lshlrev_b32_e32 v110, 3, v2
	v_and_b32_e32 v120, 0x78, v110
	v_ashrrev_i32_e32 v128, 4, v2
	v_add_f32_e32 v115, v115, v117
	v_add_f32_e32 v116, v116, v117
	v_add_f32_e32 v113, v113, v117
	v_add_f32_e32 v114, v114, v117
	v_add_f32_e32 v111, v111, v117
	v_add_f32_e32 v112, v112, v117
	v_add_f32_e32 v101, v101, v117
	v_add_f32_e32 v109, v109, v117
	v_add_f32_e32 v99, v99, v117
	v_add_f32_e32 v100, v100, v117
	v_add_f32_e32 v97, v97, v117
	v_add_f32_e32 v98, v98, v117
	v_add_f32_e32 v95, v95, v117
	v_add_f32_e32 v96, v96, v117
	v_add_f32_e32 v90, v90, v117
	v_add_f32_e32 v91, v91, v117
	v_lshl_add_u32 v110, v120, 2, 0
	ds_write2st64_b32 v0, v115, v116 offset1:2
	v_xor_b32_e32 v237, 16, v0
	ds_write2st64_b32 v237, v113, v114 offset0:4 offset1:6
	v_xor_b32_e32 v236, 32, v0
	ds_write2st64_b32 v236, v111, v112 offset0:8 offset1:10
	v_xor_b32_e32 v237, 48, v0
	ds_write2st64_b32 v237, v101, v109 offset0:12 offset1:14
	ds_write2st64_b32 v0, v99, v100 offset0:16 offset1:18
	v_xor_b32_e32 v236, 16, v0
	ds_write2st64_b32 v236, v97, v98 offset0:20 offset1:22
	v_xor_b32_e32 v237, 32, v0
	ds_write2st64_b32 v237, v95, v96 offset0:24 offset1:26
	v_xor_b32_e32 v236, 48, v0
	ds_write2st64_b32 v236, v90, v91 offset0:28 offset1:30
	v_lshlrev_b32_e32 v0, 9, v128
	v_add_u32_e32 v114, v110, v0
	s_waitcnt lgkmcnt(0)
	s_barrier
	v_xor_b32_e32 v237, 48, v110
	ds_read_b128 v[96:99], v237 offset:32256
	v_lshrrev_b32_e32 v236, 1, v204
	v_and_b32_e32 v236, 0x30, v236
	v_xor_b32_e32 v236, v236, v114
	ds_read_b128 v[116:119], v236
	v_lshlrev_b32_e32 v90, 1, v120
	v_xor_b32_e32 v237, 32, v110
	ds_read_b128 v[120:123], v237 offset:32256
	v_lshrrev_b32_e32 v236, 1, v204
	v_and_b32_e32 v236, 0x30, v236
	v_xor_b32_e32 v236, 16, v236
	v_xor_b32_e32 v236, v236, v114
	ds_read_b128 v[124:127], v236
	v_sub_u32_e32 v95, v110, v90
	v_lshlrev_b32_e32 v82, 16, v44
	s_waitcnt lgkmcnt(2)
	v_sub_f32_e32 v90, v96, v116
	v_sub_f32_e32 v91, v97, v117
	s_waitcnt lgkmcnt(0)
	v_sub_f32_e32 v109, v120, v124
	v_mul_f32_e32 v109, 0x3fb8aa3b, v109
	v_exp_f32_e32 v112, v109
	v_sub_f32_e32 v109, v121, v125
	v_mul_f32_e32 v109, 0x3fb8aa3b, v109
	v_exp_f32_e32 v113, v109
	v_sub_f32_e32 v109, v122, v126
	v_mul_f32_e32 v109, 0x3fb8aa3b, v109
	v_mul_f32_e32 v90, 0x3fb8aa3b, v90
	v_mul_f32_e32 v91, 0x3fb8aa3b, v91
	v_sub_f32_e32 v100, v98, v118
	v_sub_f32_e32 v101, v99, v119
	v_exp_f32_e32 v116, v109
	v_sub_f32_e32 v109, v123, v127
	v_exp_f32_e32 v90, v90
	v_exp_f32_e32 v91, v91
	v_mul_f32_e32 v100, 0x3fb8aa3b, v100
	v_mul_f32_e32 v101, 0x3fb8aa3b, v101
	v_mul_f32_e32 v109, 0x3fb8aa3b, v109
	v_exp_f32_e32 v100, v100
	v_exp_f32_e32 v101, v101
	v_exp_f32_e32 v117, v109
	v_and_b32_e32 v83, 0xffff0000, v44
	v_lshlrev_b32_e32 v84, 16, v45
	v_and_b32_e32 v85, 0xffff0000, v45
	v_lshlrev_b32_e32 v86, 16, v46
	v_and_b32_e32 v87, 0xffff0000, v46
	v_lshlrev_b32_e32 v88, 16, v47
	v_and_b32_e32 v89, 0xffff0000, v47
	v_pk_mul_f32 v[90:91], v[90:91], v[82:83]
	v_pk_mul_f32 v[100:101], v[100:101], v[84:85]
	v_pk_mul_f32 v[112:113], v[112:113], v[86:87]
	v_pk_mul_f32 v[124:125], v[116:117], v[88:89]
	v_cvt_pk_bf16_f32 v116, v90, v91
	v_mul_lo_u32 v90, v128, s55
	v_cvt_pk_bf16_f32 v117, v100, v101
	v_cvt_pk_bf16_f32 v118, v112, v113
	v_cvt_pk_bf16_f32 v119, v124, v125
	v_add_u32_e32 v109, v95, v90
	v_add_u32_e32 v0, 0x4000, v0
	ds_write_b128 v109, v[116:119] offset:32768
	v_add_u32_e32 v115, v110, v0
	v_lshrrev_b32_e32 v237, 1, v204
	v_and_b32_e32 v237, 0x30, v237
	v_xor_b32_e32 v237, v237, v115
	ds_read_b128 v[116:119], v237
	v_lshrrev_b32_e32 v236, 1, v204
	v_and_b32_e32 v236, 0x30, v236
	v_xor_b32_e32 v236, 16, v236
	v_xor_b32_e32 v236, v236, v115
	ds_read_b128 v[124:127], v236
	v_lshlrev_b32_e32 v76, 16, v48
	v_and_b32_e32 v77, 0xffff0000, v48
	v_lshlrev_b32_e32 v78, 16, v49
	s_waitcnt lgkmcnt(1)
	v_sub_f32_e32 v0, v96, v116
	v_mul_f32_e32 v0, 0x3fb8aa3b, v0
	v_exp_f32_e32 v96, v0
	v_sub_f32_e32 v0, v97, v117
	v_mul_f32_e32 v0, 0x3fb8aa3b, v0
	v_exp_f32_e32 v97, v0
	v_sub_f32_e32 v0, v98, v118
	v_mul_f32_e32 v0, 0x3fb8aa3b, v0
	v_exp_f32_e32 v98, v0
	v_sub_f32_e32 v0, v99, v119
	v_mul_f32_e32 v0, 0x3fb8aa3b, v0
	v_exp_f32_e32 v99, v0
	s_waitcnt lgkmcnt(0)
	v_sub_f32_e32 v0, v120, v124
	v_mul_f32_e32 v0, 0x3fb8aa3b, v0
	v_exp_f32_e32 v100, v0
	v_sub_f32_e32 v0, v121, v125
	v_mul_f32_e32 v0, 0x3fb8aa3b, v0
	v_exp_f32_e32 v101, v0
	v_sub_f32_e32 v0, v122, v126
	v_mul_f32_e32 v0, 0x3fb8aa3b, v0
	v_exp_f32_e32 v112, v0
	v_sub_f32_e32 v0, v123, v127
	v_mul_f32_e32 v0, 0x3fb8aa3b, v0
	v_exp_f32_e32 v113, v0
	v_and_b32_e32 v79, 0xffff0000, v49
	v_lshlrev_b32_e32 v80, 16, v50
	v_and_b32_e32 v81, 0xffff0000, v50
	v_lshlrev_b32_e32 v90, 16, v51
	v_and_b32_e32 v91, 0xffff0000, v51
	v_pk_mul_f32 v[96:97], v[96:97], v[76:77]
	v_pk_mul_f32 v[98:99], v[98:99], v[78:79]
	v_pk_mul_f32 v[100:101], v[100:101], v[80:81]
	v_pk_mul_f32 v[112:113], v[112:113], v[90:91]
	s_lshl_b32 s2, s64, 9
	v_cmp_gt_i32_e64 s[12:13], s53, v2
	v_cvt_pk_bf16_f32 v96, v96, v97
	v_cvt_pk_bf16_f32 v97, v98, v99
	v_cvt_pk_bf16_f32 v98, v100, v101
	v_cvt_pk_bf16_f32 v99, v112, v113
	v_lshl_add_u32 v112, v2, 2, 0
	ds_write_b128 v109, v[96:99] offset:41984
	s_and_saveexec_b64 s[62:63], s[12:13]
	s_cbranch_execz .LBB0_1490
	v_xor_b32_e32 v237, 48, v112
	ds_read_b32 v0, v237 offset:32256
	s_ashr_i32 s57, s56, 31
	s_lshl_b64 s[72:73], s[56:57], 15
	s_add_u32 s26, s0, s72
	s_addc_u32 s57, s1, s73
	s_waitcnt lgkmcnt(0)
	v_mul_f32_e32 v0, 0x3fb8aa3b, v0
	v_exp_f32_e32 v0, v0
	s_add_u32 s72, s26, s2
	s_addc_u32 s73, s57, 0
	v_lshl_add_u64 v[96:97], v[2:3], 2, s[72:73]
	global_store_dword v[96:97], v0, off

.LBB0_1498:
	v_mfma_f32_16x16x32_bf16 v[72:75], v[56:59], v[72:75], 0
	v_or_b32_e32 v93, 0x200, v105
	v_or_b32_e32 v118, 0x400, v105
	v_or_b32_e32 v119, 0x600, v105
	v_mfma_f32_16x16x32_bf16 v[68:71], v[56:59], v[68:71], 0
	v_or_b32_e32 v120, 0x800, v105
	s_waitcnt vmcnt(8)
	s_nop 1
	v_add_f32_e32 v132, v64, v72
	v_add_f32_e32 v73, v65, v73
	v_min_f32_e32 v72, 0, v132
	v_mul_f32_e64 v132, |v132|, s49
	v_mul_f32_e64 v133, |v73|, s49
	v_add_f32_e32 v134, v66, v74
	v_add_f32_e32 v75, v67, v75
	v_exp_f32_e32 v132, v132
	v_exp_f32_e32 v133, v133
	v_min_f32_e32 v74, 0, v134
	v_mul_f32_e64 v134, |v134|, s49
	v_mul_f32_e64 v135, |v75|, s49
	v_exp_f32_e32 v134, v134
	v_exp_f32_e32 v135, v135
	v_add_f32_e32 v132, 1.0, v132
	v_add_f32_e32 v133, 1.0, v133
	v_log_f32_e32 v132, v132
	v_log_f32_e32 v133, v133
	v_add_f32_e32 v134, 1.0, v134
	v_add_f32_e32 v135, 1.0, v135
	v_log_f32_e32 v134, v134
	v_log_f32_e32 v135, v135
	v_min_f32_e32 v73, 0, v73
	v_xor_b32_e32 v133, 0x80000000, v133
	v_xor_b32_e32 v132, 0x80000000, v132
	v_min_f32_e32 v75, 0, v75
	v_pk_fma_f32 v[72:73], v[132:133], s[52:53], v[72:73] op_sel_hi:[1,0,1]
	v_xor_b32_e32 v133, 0x80000000, v135
	v_xor_b32_e32 v132, 0x80000000, v134
	v_pk_fma_f32 v[74:75], v[132:133], s[52:53], v[74:75] op_sel_hi:[1,0,1]
	v_pk_mul_f32 v[72:73], v[72:73], s[54:55] op_sel_hi:[1,0]
	v_pk_mul_f32 v[74:75], v[74:75], s[54:55] op_sel_hi:[1,0]
	v_lshlrev_b32_e32 v236, 3, v204
	v_and_b32_e32 v236, 0x30, v236
	v_xor_b32_e32 v236, v236, v108
	ds_write_b128 v236, v[72:75]
	v_add_f32_e32 v72, v64, v68
	v_add_f32_e32 v69, v65, v69
	v_min_f32_e32 v68, 0, v72
	v_mul_f32_e64 v72, |v72|, s49
	v_mul_f32_e64 v73, |v69|, s49
	v_add_f32_e32 v74, v66, v70
	v_add_f32_e32 v71, v67, v71
	v_exp_f32_e32 v72, v72
	v_exp_f32_e32 v73, v73
	v_min_f32_e32 v70, 0, v74
	v_mul_f32_e64 v74, |v74|, s49
	v_mul_f32_e64 v75, |v71|, s49
	v_exp_f32_e32 v74, v74
	v_exp_f32_e32 v75, v75
	v_add_f32_e32 v72, 1.0, v72
	v_add_f32_e32 v73, 1.0, v73
	v_log_f32_e32 v72, v72
	v_log_f32_e32 v73, v73
	v_add_f32_e32 v74, 1.0, v74
	v_add_f32_e32 v75, 1.0, v75
	v_log_f32_e32 v74, v74
	v_log_f32_e32 v75, v75
	v_mfma_f32_16x16x32_bf16 v[52:55], v[56:59], v[52:55], 0
	v_min_f32_e32 v69, 0, v69
	v_xor_b32_e32 v73, 0x80000000, v73
	v_xor_b32_e32 v72, 0x80000000, v72
	v_mfma_f32_16x16x32_bf16 v[60:63], v[56:59], v[60:63], 0
	v_min_f32_e32 v71, 0, v71
	v_pk_fma_f32 v[68:69], v[72:73], s[52:53], v[68:69] op_sel_hi:[1,0,1]
	v_xor_b32_e32 v73, 0x80000000, v75
	v_xor_b32_e32 v72, 0x80000000, v74
	v_pk_fma_f32 v[70:71], v[72:73], s[52:53], v[70:71] op_sel_hi:[1,0,1]
	v_pk_mul_f32 v[68:69], v[68:69], s[54:55] op_sel_hi:[1,0]
	v_pk_mul_f32 v[70:71], v[70:71], s[54:55] op_sel_hi:[1,0]
	v_add_f32_e32 v56, v64, v52
	v_add_f32_e32 v53, v65, v53
	v_lshlrev_b32_e32 v237, 3, v204
	v_and_b32_e32 v237, 0x30, v237
	v_xor_b32_e32 v237, v237, v108
	ds_write_b128 v237, v[68:71] offset:8192
	v_add_f32_e32 v68, v64, v60
	v_add_f32_e32 v61, v65, v61
	v_min_f32_e32 v52, 0, v56
	v_mul_f32_e64 v56, |v56|, s49
	v_mul_f32_e64 v57, |v53|, s49
	v_add_f32_e32 v58, v66, v54
	v_add_f32_e32 v55, v67, v55
	v_min_f32_e32 v60, 0, v68
	v_mul_f32_e64 v68, |v68|, s49
	v_mul_f32_e64 v69, |v61|, s49
	v_add_f32_e32 v70, v66, v62
	v_add_f32_e32 v63, v67, v63
	v_exp_f32_e32 v56, v56
	v_exp_f32_e32 v57, v57
	v_min_f32_e32 v54, 0, v58
	v_mul_f32_e64 v58, |v58|, s49
	v_mul_f32_e64 v59, |v55|, s49
	v_exp_f32_e32 v68, v68
	v_exp_f32_e32 v69, v69
	v_min_f32_e32 v62, 0, v70
	v_mul_f32_e64 v70, |v70|, s49
	v_mul_f32_e64 v71, |v63|, s49
	v_exp_f32_e32 v58, v58
	v_exp_f32_e32 v59, v59
	v_exp_f32_e32 v70, v70
	v_exp_f32_e32 v71, v71
	v_add_f32_e32 v56, 1.0, v56
	v_add_f32_e32 v57, 1.0, v57
	v_add_f32_e32 v68, 1.0, v68
	v_add_f32_e32 v69, 1.0, v69
	v_log_f32_e32 v56, v56
	v_log_f32_e32 v57, v57
	v_add_f32_e32 v58, 1.0, v58
	v_add_f32_e32 v59, 1.0, v59
	v_log_f32_e32 v68, v68
	v_log_f32_e32 v69, v69
	v_add_f32_e32 v70, 1.0, v70
	v_add_f32_e32 v71, 1.0, v71
	v_log_f32_e32 v58, v58
	v_log_f32_e32 v59, v59
	v_log_f32_e32 v70, v70
	v_log_f32_e32 v71, v71
	v_min_f32_e32 v53, 0, v53
	v_xor_b32_e32 v57, 0x80000000, v57
	v_xor_b32_e32 v56, 0x80000000, v56
	v_min_f32_e32 v61, 0, v61
	v_xor_b32_e32 v69, 0x80000000, v69
	v_xor_b32_e32 v68, 0x80000000, v68
	v_min_f32_e32 v55, 0, v55
	v_pk_fma_f32 v[52:53], v[56:57], s[52:53], v[52:53] op_sel_hi:[1,0,1]
	v_xor_b32_e32 v57, 0x80000000, v59
	v_xor_b32_e32 v56, 0x80000000, v58
	v_min_f32_e32 v63, 0, v63
	v_pk_fma_f32 v[60:61], v[68:69], s[52:53], v[60:61] op_sel_hi:[1,0,1]
	v_xor_b32_e32 v69, 0x80000000, v71
	v_xor_b32_e32 v68, 0x80000000, v70
	v_pk_fma_f32 v[54:55], v[56:57], s[52:53], v[54:55] op_sel_hi:[1,0,1]
	v_or_b32_e32 v121, 0xa00, v105
	v_or_b32_e32 v122, 0xc00, v105
	v_or_b32_e32 v123, 0xe00, v105
	v_pk_fma_f32 v[62:63], v[68:69], s[52:53], v[62:63] op_sel_hi:[1,0,1]
	v_pk_mul_f32 v[54:55], v[54:55], s[54:55] op_sel_hi:[1,0]
	v_pk_mul_f32 v[52:53], v[52:53], s[54:55] op_sel_hi:[1,0]
	v_or_b32_e32 v124, 0x1000, v105
	v_or_b32_e32 v131, 0x1e00, v105
	v_pk_mul_f32 v[62:63], v[62:63], s[54:55] op_sel_hi:[1,0]
	v_pk_mul_f32 v[60:61], v[60:61], s[54:55] op_sel_hi:[1,0]
	v_lshlrev_b32_e32 v236, 3, v204
	v_and_b32_e32 v236, 0x30, v236
	v_xor_b32_e32 v236, v236, v108
	ds_write_b128 v236, v[52:55] offset:24576
	v_sub_u32_e32 v52, v104, v105
	v_sub_u32_e32 v53, v104, v93
	v_sub_u32_e32 v54, v104, v118
	v_sub_u32_e32 v55, v104, v119
	v_sub_u32_e32 v56, v104, v120
	v_sub_u32_e32 v57, v104, v121
	v_sub_u32_e32 v58, v104, v122
	v_sub_u32_e32 v59, v104, v123
	v_or_b32_e32 v125, 0x1200, v105
	v_or_b32_e32 v126, 0x1400, v105
	v_or_b32_e32 v127, 0x1600, v105
	v_or_b32_e32 v128, 0x1800, v105
	v_or_b32_e32 v129, 0x1a00, v105
	v_or_b32_e32 v130, 0x1c00, v105
	v_lshlrev_b32_e32 v237, 3, v204
	v_and_b32_e32 v237, 0x30, v237
	v_xor_b32_e32 v237, v237, v108
	ds_write_b128 v237, v[60:63] offset:16384
	s_waitcnt lgkmcnt(0)
	s_barrier
	v_xor_b32_e32 v236, 48, v52
	ds_read_b32 v52, v236 offset:32256
	v_xor_b32_e32 v237, 48, v53
	ds_read_b32 v53, v237 offset:32256
	v_xor_b32_e32 v236, 32, v54
	ds_read_b32 v54, v236 offset:32256
	v_xor_b32_e32 v237, 32, v55
	ds_read_b32 v55, v237 offset:32256
	v_xor_b32_e32 v236, 16, v56
	ds_read_b32 v56, v236 offset:32256
	v_xor_b32_e32 v237, 16, v57
	ds_read_b32 v57, v237 offset:32256
	ds_read_b32 v58, v58 offset:32256
	ds_read_b32 v59, v59 offset:32256
	v_sub_u32_e32 v60, v104, v124
	v_sub_u32_e32 v67, v104, v131
	s_waitcnt lgkmcnt(7)
	v_add_f32_e32 v68, 0, v52
	v_sub_u32_e32 v61, v104, v125
	v_sub_u32_e32 v62, v104, v126
	v_sub_u32_e32 v63, v104, v127
	v_sub_u32_e32 v64, v104, v128
	v_sub_u32_e32 v65, v104, v129
	v_sub_u32_e32 v66, v104, v130
	v_xor_b32_e32 v236, 48, v60
	ds_read_b32 v60, v236 offset:32256
	v_xor_b32_e32 v237, 48, v61
	ds_read_b32 v69, v237 offset:32256
	v_xor_b32_e32 v236, 32, v62
	ds_read_b32 v70, v236 offset:32256
	v_xor_b32_e32 v237, 32, v63
	ds_read_b32 v71, v237 offset:32256
	v_xor_b32_e32 v236, 16, v64
	ds_read_b32 v72, v236 offset:32256
	v_xor_b32_e32 v237, 16, v65
	ds_read_b32 v73, v237 offset:32256
	ds_read_b32 v74, v66 offset:32256
	ds_read_b32 v75, v67 offset:32256
	s_waitcnt lgkmcnt(14)
	v_add_f32_e32 v67, v68, v53
	s_waitcnt lgkmcnt(13)
	v_add_f32_e32 v66, v67, v54
	s_waitcnt lgkmcnt(12)
	v_add_f32_e32 v65, v66, v55
	s_waitcnt lgkmcnt(11)
	v_add_f32_e32 v64, v65, v56
	s_waitcnt lgkmcnt(10)
	v_add_f32_e32 v63, v64, v57
	s_waitcnt lgkmcnt(9)
	v_add_f32_e32 v62, v63, v58
	s_waitcnt lgkmcnt(8)
	v_add_f32_e32 v61, v62, v59
	s_waitcnt lgkmcnt(7)
	v_add_f32_e32 v60, v61, v60
	s_waitcnt lgkmcnt(6)
	v_add_f32_e32 v59, v60, v69
	s_waitcnt lgkmcnt(5)
	v_add_f32_e32 v58, v59, v70
	s_waitcnt lgkmcnt(4)
	v_add_f32_e32 v57, v58, v71
	s_waitcnt lgkmcnt(3)
	v_add_f32_e32 v55, v57, v72
	s_waitcnt lgkmcnt(2)
	v_add_f32_e32 v54, v55, v73
	s_waitcnt lgkmcnt(1)
	v_add_f32_e32 v53, v54, v74
	s_waitcnt lgkmcnt(0)
	v_add_f32_e32 v52, v53, v75
	v_mov_b32_e32 v56, 0
	ds_write_b32 v107, v52
	s_waitcnt lgkmcnt(0)
	s_barrier
	s_and_saveexec_b64 s[56:57], s[10:11]
	s_cbranch_execnz .LBB0_1510
	s_or_b64 exec, exec, s[56:57]
	s_and_saveexec_b64 s[10:11], s[14:15]
	s_cbranch_execnz .LBB0_1511

.LBB0_1502:
	s_or_b64 exec, exec, s[10:11]
	v_sub_u32_e32 v69, 0, v105
	v_sub_u32_e32 v70, 0, v93
	v_add_f32_e32 v68, v68, v56
	v_add_u32_e32 v69, v104, v69
	v_sub_u32_e32 v71, 0, v118
	v_xor_b32_e32 v236, 48, v69
	ds_write_b32 v236, v68 offset:32256
	v_add_f32_e32 v67, v67, v56
	v_add_u32_e32 v68, v104, v70
	v_sub_u32_e32 v72, 0, v119
	v_xor_b32_e32 v237, 48, v68
	ds_write_b32 v237, v67 offset:32256
	v_add_f32_e32 v66, v66, v56
	v_add_u32_e32 v67, v104, v71
	v_sub_u32_e32 v73, 0, v120
	v_xor_b32_e32 v236, 32, v67
	ds_write_b32 v236, v66 offset:32256
	v_add_f32_e32 v65, v65, v56
	v_add_u32_e32 v66, v104, v72
	v_sub_u32_e32 v74, 0, v121
	v_xor_b32_e32 v237, 32, v66
	ds_write_b32 v237, v65 offset:32256
	v_add_f32_e32 v64, v64, v56
	v_add_u32_e32 v65, v104, v73
	v_sub_u32_e32 v75, 0, v122
	v_xor_b32_e32 v236, 16, v65
	ds_write_b32 v236, v64 offset:32256
	v_add_f32_e32 v63, v63, v56
	v_add_u32_e32 v64, v104, v74
	v_sub_u32_e32 v93, 0, v123
	v_xor_b32_e32 v237, 16, v64
	ds_write_b32 v237, v63 offset:32256
	v_add_f32_e32 v62, v62, v56
	v_add_u32_e32 v63, v104, v75
	v_sub_u32_e32 v105, 0, v124
	ds_write_b32 v63, v62 offset:32256
	v_add_f32_e32 v61, v61, v56
	v_add_u32_e32 v62, v104, v93
	v_sub_u32_e32 v106, 0, v125
	ds_write_b32 v62, v61 offset:32256
	v_add_f32_e32 v60, v60, v56
	v_add_u32_e32 v61, v104, v105
	v_sub_u32_e32 v107, 0, v126
	v_xor_b32_e32 v236, 48, v61
	ds_write_b32 v236, v60 offset:32256
	v_add_f32_e32 v59, v59, v56
	v_add_u32_e32 v60, v104, v106
	v_sub_u32_e32 v108, 0, v127
	v_xor_b32_e32 v237, 48, v60
	ds_write_b32 v237, v59 offset:32256
	v_add_f32_e32 v58, v58, v56
	v_add_u32_e32 v59, v104, v107
	v_sub_u32_e32 v118, 0, v128
	v_xor_b32_e32 v236, 32, v59
	ds_write_b32 v236, v58 offset:32256
	v_add_f32_e32 v57, v57, v56
	v_add_u32_e32 v58, v104, v108
	v_sub_u32_e32 v119, 0, v129
	v_xor_b32_e32 v237, 32, v58
	ds_write_b32 v237, v57 offset:32256
	v_add_f32_e32 v55, v55, v56
	v_add_u32_e32 v57, v104, v118
	v_sub_u32_e32 v120, 0, v130
	v_xor_b32_e32 v236, 16, v57
	ds_write_b32 v236, v55 offset:32256
	v_add_f32_e32 v54, v54, v56
	v_add_u32_e32 v55, v104, v119
	v_sub_u32_e32 v121, 0, v131
	v_xor_b32_e32 v237, 16, v55
	ds_write_b32 v237, v54 offset:32256
	v_add_f32_e32 v53, v53, v56
	v_add_u32_e32 v54, v104, v120
	ds_write_b32 v54, v53 offset:32256
	v_add_f32_e32 v52, v52, v56
	v_add_u32_e32 v53, v104, v121
	ds_write_b32 v53, v52 offset:32256
	s_waitcnt lgkmcnt(0)
	s_barrier
	v_lshrrev_b32_e32 v236, 1, v204
	v_and_b32_e32 v236, 0x30, v236
	v_xor_b32_e32 v236, v236, v114
	ds_read_b128 v[52:55], v236
	ds_read_b128 v[56:59], v110
	v_xor_b32_e32 v237, 16, v110
	ds_read_b128 v[60:63], v237
	v_lshrrev_b32_e32 v236, 1, v204
	v_and_b32_e32 v236, 0x30, v236
	v_xor_b32_e32 v236, 16, v236
	v_xor_b32_e32 v236, v236, v114
	ds_read_b128 v[64:67], v236
	s_waitcnt lgkmcnt(2)
	v_sub_f32_e32 v52, v56, v52
	v_sub_f32_e32 v53, v57, v53
	v_sub_f32_e32 v54, v58, v54
	v_sub_f32_e32 v55, v59, v55
	s_waitcnt lgkmcnt(0)
	v_sub_f32_e32 v64, v60, v64
	v_sub_f32_e32 v65, v61, v65
	v_sub_f32_e32 v66, v62, v66
	v_sub_f32_e32 v67, v63, v67
	v_mul_f32_e32 v52, 0x3fb8aa3b, v52
	v_mul_f32_e32 v53, 0x3fb8aa3b, v53
	v_mul_f32_e32 v54, 0x3fb8aa3b, v54
	v_mul_f32_e32 v55, 0x3fb8aa3b, v55
	v_mul_f32_e32 v64, 0x3fb8aa3b, v64
	v_mul_f32_e32 v65, 0x3fb8aa3b, v65
	v_mul_f32_e32 v66, 0x3fb8aa3b, v66
	v_mul_f32_e32 v67, 0x3fb8aa3b, v67
	v_exp_f32_e32 v52, v52
	v_exp_f32_e32 v53, v53
	v_exp_f32_e32 v54, v54
	v_exp_f32_e32 v55, v55
	v_exp_f32_e32 v64, v64
	v_exp_f32_e32 v65, v65
	v_exp_f32_e32 v66, v66
	v_exp_f32_e32 v67, v67
	v_pk_mul_f32 v[52:53], v[52:53], v[82:83]
	v_pk_mul_f32 v[54:55], v[54:55], v[84:85]
	v_pk_mul_f32 v[64:65], v[64:65], v[86:87]
	v_pk_mul_f32 v[66:67], v[66:67], v[88:89]
	v_cvt_pk_bf16_f32 v52, v52, v53
	v_cvt_pk_bf16_f32 v53, v54, v55
	v_cvt_pk_bf16_f32 v54, v64, v65
	v_cvt_pk_bf16_f32 v55, v66, v67
	ds_write_b128 v109, v[52:55] offset:32768
	v_lshrrev_b32_e32 v237, 1, v204
	v_and_b32_e32 v237, 0x30, v237
	v_xor_b32_e32 v237, v237, v115
	ds_read_b128 v[52:55], v237
	v_lshrrev_b32_e32 v236, 1, v204
	v_and_b32_e32 v236, 0x30, v236
	v_xor_b32_e32 v236, 16, v236
	v_xor_b32_e32 v236, v236, v115
	ds_read_b128 v[64:67], v236
	s_waitcnt lgkmcnt(1)
	v_sub_f32_e32 v52, v56, v52
	v_sub_f32_e32 v53, v57, v53
	v_sub_f32_e32 v54, v58, v54
	v_sub_f32_e32 v55, v59, v55
	s_waitcnt lgkmcnt(0)
	v_sub_f32_e32 v56, v60, v64
	v_sub_f32_e32 v57, v61, v65
	v_sub_f32_e32 v58, v62, v66
	v_sub_f32_e32 v59, v63, v67
	v_mul_f32_e32 v52, 0x3fb8aa3b, v52
	v_mul_f32_e32 v53, 0x3fb8aa3b, v53
	v_mul_f32_e32 v54, 0x3fb8aa3b, v54
	v_mul_f32_e32 v55, 0x3fb8aa3b, v55
	v_mul_f32_e32 v56, 0x3fb8aa3b, v56
	v_mul_f32_e32 v57, 0x3fb8aa3b, v57
	v_mul_f32_e32 v58, 0x3fb8aa3b, v58
	v_mul_f32_e32 v59, 0x3fb8aa3b, v59
	v_exp_f32_e32 v52, v52
	v_exp_f32_e32 v53, v53
	v_exp_f32_e32 v54, v54
	v_exp_f32_e32 v55, v55
	v_exp_f32_e32 v56, v56
	v_exp_f32_e32 v57, v57
	v_exp_f32_e32 v58, v58
	v_exp_f32_e32 v59, v59
	v_pk_mul_f32 v[52:53], v[52:53], v[76:77]
	v_pk_mul_f32 v[54:55], v[54:55], v[78:79]
	v_pk_mul_f32 v[56:57], v[56:57], v[80:81]
	v_pk_mul_f32 v[58:59], v[58:59], v[90:91]
	v_cvt_pk_bf16_f32 v52, v52, v53
	v_cvt_pk_bf16_f32 v53, v54, v55
	v_cvt_pk_bf16_f32 v54, v56, v57
	v_cvt_pk_bf16_f32 v55, v58, v59
	ds_write_b128 v109, v[52:55] offset:41984
	s_and_saveexec_b64 s[10:11], s[12:13]
	s_cbranch_execz .LBB0_1433
	v_lshrrev_b32_e32 v237, 4, v204
	v_and_b32_e32 v237, 0x30, v237
	v_xor_b32_e32 v237, v237, v112
	ds_read_b32 v52, v237
	s_ashr_i32 s63, s62, 31
	s_lshl_b64 s[12:13], s[62:63], 15
	s_add_u32 s12, s0, s12
	s_addc_u32 s13, s1, s13
	s_waitcnt lgkmcnt(0)
	v_mul_f32_e32 v52, 0x3fb8aa3b, v52
	v_exp_f32_e32 v52, v52
	s_add_u32 s12, s12, s2
	s_addc_u32 s13, s13, 0
	v_lshl_add_u64 v[2:3], v[2:3], 2, s[12:13]
	global_store_dword v[2:3], v52, off
	s_branch .LBB0_1433
